# GEMM K-loops: last 2 of the 6 LDS-DMA pieces of each second super-phase issued between that super-phase's MFMAs instead of in its load segment; counted vmcnt waits re-derived (8,6,8,6)
# baseline (speedup 1.0000x reference)
; #define PG8_STAGE(bufoff, gbase, voff) do { if constexpr (DIAG >= 1) break; _Pragma("unroll") for (int _i = 0; _i < 2; ++_i) \
;         __builtin_amdgcn_global_load_lds((const unsigned*)((const char*)(gbase) + (voff)[_i]), (PG8_LAS unsigned*)(lds + (bufoff) + ldsw + _i * 8192), 16, 0, 0); } while (0)
; #define PG8_LDA(dst, b, h) do { if constexpr (DIAG == 2 || DIAG == 3) break; _Pragma("unroll") for (int m = 0; m < 4; ++m) _Pragma("unroll") for (int k = 0; k < 2; ++k) dst[m][k] = *(const PG8_LAS bf16x8*)(lds + PG8_SA(b, h) + aoff + m * 2048 + k * 1024); } while (0)
; #define PG8_LDB(dst, b, h) do { if constexpr (DIAG == 2 || DIAG == 3) break; _Pragma("unroll") for (int n = 0; n < 2; ++n) _Pragma("unroll") for (int k = 0; k < 2; ++k) dst[n][k] = *(const PG8_LAS bf16x8*)(lds + PG8_SB(b, h) + boff + n * 2048 + k * 1024); } while (0)
; #define PG8_WAIT_V(n) asm volatile("s_waitcnt vmcnt(" #n ")" ::: "memory")
; #define PG8_WAIT_L(n) asm volatile("s_waitcnt lgkmcnt(" #n ")" ::: "memory")
; #define PG8_BAR __builtin_amdgcn_s_barrier()
; #define PG8_LP_ON __builtin_amdgcn_s_setprio(PG8_LOADPRIO)
; #define PG8_LP_OFF __builtin_amdgcn_s_setprio(0)
; #define PG8_LP_ON do {} while (0)
; #define PG8_LP_OFF do {} while (0)
;     ...
;             if constexpr (SP2) {
;             PG8_LP_ON; PG8_LDB(B0, 0, 0); PG8_LDB(B1, 0, 1); PG8_SCHED; PG8_LDA(At, 0, 0); PG8_STAGE(PG8_SA(1, 1), a1 + hstep, voffA);
;             PG8_LP_OFF; PG8_WAIT_V(8); PG8_WAIT_L(0); PG8_BAR; PG8_MMA(0, 0, At, B0); PG8_MMA(0, 1, At, B1); PG8_BAR; PG8_SCHED;
;             PG8_LP_ON; PG8_LDA(At, 0, 1); PG8_STAGE(PG8_SB(0, 0), b2, voffB); PG8_STAGE(PG8_SB(0, 1), b2 + hstep, voffB); PG8_STAGE(PG8_SA(0, 0), a2, voffA);
;             PG8_LP_OFF; PG8_WAIT_V(8); PG8_WAIT_L(0); PG8_BAR; PG8_MMA(1, 0, At, B0); PG8_MMA(1, 1, At, B1); PG8_BAR; PG8_SCHED;
;             PG8_LP_ON; PG8_LDB(B0, 1, 0); PG8_LDB(B1, 1, 1); PG8_SCHED; PG8_LDA(At, 1, 0); PG8_STAGE(PG8_SA(0, 1), a2 + hstep, voffA);
;             PG8_LP_OFF; PG8_WAIT_V(8); PG8_WAIT_L(0); PG8_BAR; PG8_MMA(0, 0, At, B0); PG8_MMA(0, 1, At, B1); PG8_BAR; PG8_SCHED;
;             PG8_LP_ON; PG8_LDA(At, 1, 1); PG8_STAGE(PG8_SB(1, 0), b3, voffB); PG8_STAGE(PG8_SB(1, 1), b3 + hstep, voffB); PG8_STAGE(PG8_SA(1, 0), a3, voffA);
;             PG8_LP_OFF; PG8_WAIT_V(8); PG8_WAIT_L(0); PG8_BAR; PG8_MMA(1, 0, At, B0); PG8_MMA(1, 1, At, B1); PG8_BAR; PG8_SCHED;
.LBB0_225:
	ds_read_b128 v[26:29], v192
	ds_read_b128 v[30:33], v192 offset:1024
	ds_read_b128 v[18:21], v192 offset:2048
	ds_read_b128 v[22:25], v192 offset:3072
	ds_read_b128 v[10:13], v193
	ds_read_b128 v[14:17], v193 offset:1024
	ds_read_b128 v[2:5], v193 offset:2048
	ds_read_b128 v[6:9], v193 offset:3072
	ds_read_b128 v[182:185], v194
	ds_read_b128 v[186:189], v194 offset:1024
	ds_read_b128 v[196:199], v194 offset:2048
	ds_read_b128 v[200:203], v194 offset:3072
	ds_read_b128 v[204:207], v194 offset:4096
	ds_read_b128 v[208:211], v194 offset:5120
	ds_read_b128 v[212:215], v194 offset:6144
	ds_read_b128 v[216:219], v194 offset:7168
	s_add_u32 s77, s86, 0xfff80080
	s_addc_u32 s78, s87, -1
	s_cmp_eq_u32 s76, 28
	s_cselect_b32 s91, s23, s78
	s_cselect_b32 s90, vcc_lo, s77
	s_cselect_b32 s89, s21, s75
	s_cselect_b32 s88, vcc_hi, s74
	v_lshl_add_u64 v[220:221], s[86:87], 0, v[174:175]
	s_add_i32 m0, s19, 0xc000
	s_nop 0
	global_load_lds_dwordx4 v[220:221], off
	v_lshl_add_u64 v[220:221], s[86:87], 0, v[176:177]
	s_add_i32 m0, s19, 0xe000
	s_nop 0
	global_load_lds_dwordx4 v[220:221], off
	s_waitcnt vmcnt(8)
	s_waitcnt lgkmcnt(0)
	s_barrier
	s_setprio 1
	s_waitcnt lgkmcnt(0)
	v_mfma_f32_16x16x128_f8f6f4 v[158:161], v[26:33], v[182:189], v[158:161]
	v_mfma_f32_16x16x128_f8f6f4 v[154:157], v[18:25], v[182:189], v[154:157]
	v_mfma_f32_16x16x128_f8f6f4 v[142:145], v[26:33], v[196:203], v[142:145]
	v_mfma_f32_16x16x128_f8f6f4 v[138:141], v[18:25], v[196:203], v[138:141]
	v_mfma_f32_16x16x128_f8f6f4 v[126:129], v[26:33], v[204:211], v[126:129]
	v_mfma_f32_16x16x128_f8f6f4 v[122:125], v[18:25], v[204:211], v[122:125]
	v_mfma_f32_16x16x128_f8f6f4 v[110:113], v[26:33], v[212:219], v[110:113]
	v_mfma_f32_16x16x128_f8f6f4 v[106:109], v[18:25], v[212:219], v[106:109]
	s_setprio 0
	s_setprio 1
	v_mfma_f32_16x16x128_f8f6f4 v[150:153], v[10:17], v[182:189], v[150:153]
	v_mfma_f32_16x16x128_f8f6f4 v[146:149], v[2:9], v[182:189], v[146:149]
	v_mfma_f32_16x16x128_f8f6f4 v[134:137], v[10:17], v[196:203], v[134:137]
	v_mfma_f32_16x16x128_f8f6f4 v[130:133], v[2:9], v[196:203], v[130:133]
	v_mfma_f32_16x16x128_f8f6f4 v[118:121], v[10:17], v[204:211], v[118:121]
	v_mfma_f32_16x16x128_f8f6f4 v[114:117], v[2:9], v[204:211], v[114:117]
	v_mfma_f32_16x16x128_f8f6f4 v[102:105], v[10:17], v[212:219], v[102:105]
	v_mfma_f32_16x16x128_f8f6f4 v[98:101], v[2:9], v[212:219], v[98:101]
	s_setprio 0
	s_barrier
	ds_read_b128 v[196:199], v194 offset:16384
	ds_read_b128 v[200:203], v194 offset:17408
	ds_read_b128 v[204:207], v194 offset:18432
	ds_read_b128 v[208:211], v194 offset:19456
	ds_read_b128 v[212:215], v194 offset:20480
	ds_read_b128 v[216:219], v194 offset:21504
	ds_read_b128 v[220:223], v194 offset:22528
	ds_read_b128 v[224:227], v194 offset:23552
	s_add_i32 s77, s95, s0
	v_lshl_add_u64 v[182:183], s[88:89], 0, v[168:169]
	s_mov_b32 m0, s77
	s_nop 0
	global_load_lds_dwordx4 v[182:183], off
	s_add_i32 m0, s77, 0x2000
	s_add_u32 s78, s88, 0x80000
	v_lshl_add_u64 v[184:185], s[88:89], 0, v[172:173]
	s_addc_u32 s79, s89, 0
	s_add_i32 s77, s96, s0
	global_load_lds_dwordx4 v[184:185], off
	v_lshl_add_u64 v[186:187], s[78:79], 0, v[168:169]
	s_mov_b32 m0, s77
	v_lshl_add_u64 v[188:189], s[90:91], 0, v[170:171]
	global_load_lds_dwordx4 v[186:187], off
	v_lshl_add_u64 v[186:187], s[78:79], 0, v[172:173]
	s_add_i32 m0, s77, 0x2000
	s_nop 0
	global_load_lds_dwordx4 v[186:187], off
	s_waitcnt vmcnt(6)
	s_waitcnt lgkmcnt(0)
	s_barrier
	s_setprio 1
	s_waitcnt lgkmcnt(0)
	v_mfma_f32_16x16x128_f8f6f4 v[94:97], v[26:33], v[196:203], v[94:97]
	v_mfma_f32_16x16x128_f8f6f4 v[90:93], v[18:25], v[196:203], v[90:93]
	v_mfma_f32_16x16x128_f8f6f4 v[78:81], v[26:33], v[204:211], v[78:81]
	v_mfma_f32_16x16x128_f8f6f4 v[74:77], v[18:25], v[204:211], v[74:77]
	v_mfma_f32_16x16x128_f8f6f4 v[62:65], v[26:33], v[212:219], v[62:65]
	v_lshl_add_u64 v[186:187], s[90:91], 0, v[166:167]
	s_mov_b32 m0, s19
	s_nop 0
	global_load_lds_dwordx4 v[186:187], off
	v_mfma_f32_16x16x128_f8f6f4 v[58:61], v[18:25], v[212:219], v[58:61]
	v_mfma_f32_16x16x128_f8f6f4 v[46:49], v[26:33], v[220:227], v[46:49]
	v_mfma_f32_16x16x128_f8f6f4 v[42:45], v[18:25], v[220:227], v[42:45]
	s_setprio 0
	s_setprio 1
	v_mfma_f32_16x16x128_f8f6f4 v[86:89], v[10:17], v[196:203], v[86:89]
	v_mfma_f32_16x16x128_f8f6f4 v[82:85], v[2:9], v[196:203], v[82:85]
	v_mfma_f32_16x16x128_f8f6f4 v[70:73], v[10:17], v[204:211], v[70:73]
	v_mfma_f32_16x16x128_f8f6f4 v[66:69], v[2:9], v[204:211], v[66:69]
	v_mfma_f32_16x16x128_f8f6f4 v[54:57], v[10:17], v[212:219], v[54:57]
	s_mov_b32 m0, s34
	s_nop 0
	global_load_lds_dwordx4 v[188:189], off
	v_mfma_f32_16x16x128_f8f6f4 v[50:53], v[2:9], v[212:219], v[50:53]
	v_mfma_f32_16x16x128_f8f6f4 v[38:41], v[10:17], v[220:227], v[38:41]
	v_mfma_f32_16x16x128_f8f6f4 v[34:37], v[2:9], v[220:227], v[34:37]
	s_setprio 0
	s_barrier
; #define PG8_STAGE(bufoff, gbase, voff) do { if constexpr (DIAG >= 1) break; _Pragma("unroll") for (int _i = 0; _i < 2; ++_i) \
;         __builtin_amdgcn_global_load_lds((const unsigned*)((const char*)(gbase) + (voff)[_i]), (PG8_LAS unsigned*)(lds + (bufoff) + ldsw + _i * 8192), 16, 0, 0); } while (0)
; #define PG8_LDA(dst, b, h) do { if constexpr (DIAG == 2 || DIAG == 3) break; _Pragma("unroll") for (int m = 0; m < 4; ++m) _Pragma("unroll") for (int k = 0; k < 2; ++k) dst[m][k] = *(const PG8_LAS bf16x8*)(lds + PG8_SA(b, h) + aoff + m * 2048 + k * 1024); } while (0)
; #define PG8_LDB(dst, b, h) do { if constexpr (DIAG == 2 || DIAG == 3) break; _Pragma("unroll") for (int n = 0; n < 2; ++n) _Pragma("unroll") for (int k = 0; k < 2; ++k) dst[n][k] = *(const PG8_LAS bf16x8*)(lds + PG8_SB(b, h) + boff + n * 2048 + k * 1024); } while (0)
; #define PG8_WAIT_V(n) asm volatile("s_waitcnt vmcnt(" #n ")" ::: "memory")
; #define PG8_WAIT_L(n) asm volatile("s_waitcnt lgkmcnt(" #n ")" ::: "memory")
; #define PG8_BAR __builtin_amdgcn_s_barrier()
; #define PG8_LP_ON __builtin_amdgcn_s_setprio(PG8_LOADPRIO)
; #define PG8_LP_OFF __builtin_amdgcn_s_setprio(0)
; #define PG8_LP_ON do {} while (0)
; #define PG8_LP_OFF do {} while (0)
; #define PG8_SCHED __builtin_amdgcn_sched_barrier(0)
;     ...
;             PG8_LP_ON; PG8_LDB(B0, 1, 0); PG8_LDB(B1, 1, 1); PG8_SCHED; PG8_LDA(At, 1, 0); PG8_STAGE(PG8_SA(0, 1), a2 + hstep, voffA);
;             PG8_LP_OFF; PG8_WAIT_V(8); PG8_WAIT_L(0); PG8_BAR; PG8_MMA(0, 0, At, B0); PG8_MMA(0, 1, At, B1); PG8_BAR; PG8_SCHED;
;             PG8_LP_ON; PG8_LDA(At, 1, 1); PG8_STAGE(PG8_SB(1, 0), b3, voffB); PG8_STAGE(PG8_SB(1, 1), b3 + hstep, voffB); PG8_STAGE(PG8_SA(1, 0), a3, voffA);
;             PG8_LP_OFF; PG8_WAIT_V(8); PG8_WAIT_L(0); PG8_BAR; PG8_MMA(1, 0, At, B0); PG8_MMA(1, 1, At, B1); PG8_BAR; PG8_SCHED;
	s_add_i32 s77, 0, 0x18000
	s_add_i32 s80, 0, 0x1c000
	v_add_u32_e32 v14, s77, v190
	v_add_u32_e32 v30, s80, v190
	ds_read_b128 v[2:5], v14
	ds_read_b128 v[6:9], v14 offset:1024
	ds_read_b128 v[10:13], v14 offset:2048
	ds_read_b128 v[14:17], v14 offset:3072
	ds_read_b128 v[18:21], v30
	ds_read_b128 v[22:25], v30 offset:1024
	ds_read_b128 v[26:29], v30 offset:2048
	ds_read_b128 v[30:33], v30 offset:3072
	ds_read_b128 v[196:199], v194 offset:32768
	ds_read_b128 v[200:203], v194 offset:33792
	ds_read_b128 v[204:207], v194 offset:34816
	ds_read_b128 v[208:211], v194 offset:35840
	ds_read_b128 v[212:215], v194 offset:36864
	ds_read_b128 v[216:219], v194 offset:37888
	ds_read_b128 v[220:223], v194 offset:38912
	ds_read_b128 v[224:227], v194 offset:39936
	s_add_u32 s78, s90, 0x80000
	s_addc_u32 s79, s91, 0
	s_mov_b32 m0, s73
	v_lshl_add_u64 v[228:229], s[78:79], 0, v[166:167]
	global_load_lds_dwordx4 v[228:229], off
	v_lshl_add_u64 v[228:229], s[78:79], 0, v[170:171]
	s_mov_b32 m0, s84
	s_nop 0
	global_load_lds_dwordx4 v[228:229], off
	s_waitcnt vmcnt(8)
	s_waitcnt lgkmcnt(0)
	s_barrier
	s_setprio 1
	s_waitcnt lgkmcnt(0)
	v_mfma_f32_16x16x128_f8f6f4 v[158:161], v[2:9], v[196:203], v[158:161]
	v_mfma_f32_16x16x128_f8f6f4 v[154:157], v[10:17], v[196:203], v[154:157]
	v_mfma_f32_16x16x128_f8f6f4 v[142:145], v[2:9], v[204:211], v[142:145]
	v_mfma_f32_16x16x128_f8f6f4 v[138:141], v[10:17], v[204:211], v[138:141]
	v_mfma_f32_16x16x128_f8f6f4 v[126:129], v[2:9], v[212:219], v[126:129]
	v_mfma_f32_16x16x128_f8f6f4 v[122:125], v[10:17], v[212:219], v[122:125]
	v_mfma_f32_16x16x128_f8f6f4 v[110:113], v[2:9], v[220:227], v[110:113]
	v_mfma_f32_16x16x128_f8f6f4 v[106:109], v[10:17], v[220:227], v[106:109]
	s_setprio 0
	s_setprio 1
	v_mfma_f32_16x16x128_f8f6f4 v[150:153], v[18:25], v[196:203], v[150:153]
	v_mfma_f32_16x16x128_f8f6f4 v[146:149], v[26:33], v[196:203], v[146:149]
	v_mfma_f32_16x16x128_f8f6f4 v[134:137], v[18:25], v[204:211], v[134:137]
	v_mfma_f32_16x16x128_f8f6f4 v[130:133], v[26:33], v[204:211], v[130:133]
	v_mfma_f32_16x16x128_f8f6f4 v[118:121], v[18:25], v[212:219], v[118:121]
	v_mfma_f32_16x16x128_f8f6f4 v[114:117], v[26:33], v[212:219], v[114:117]
	v_mfma_f32_16x16x128_f8f6f4 v[102:105], v[18:25], v[220:227], v[102:105]
	v_mfma_f32_16x16x128_f8f6f4 v[98:101], v[26:33], v[220:227], v[98:101]
	s_setprio 0
	s_barrier
	ds_read_b128 v[196:199], v194 offset:49152
	ds_read_b128 v[200:203], v194 offset:50176
	ds_read_b128 v[204:207], v194 offset:51200
	ds_read_b128 v[208:211], v194 offset:52224
	ds_read_b128 v[212:215], v194 offset:53248
	ds_read_b128 v[216:219], v194 offset:54272
	ds_read_b128 v[220:223], v194 offset:55296
	ds_read_b128 v[224:227], v194 offset:56320
	s_add_i32 s77, s77, s0
	v_lshl_add_u64 v[182:183], v[182:183], 0, s[12:13]
	s_mov_b32 m0, s77
	s_nop 0
	global_load_lds_dwordx4 v[182:183], off
	s_add_i32 m0, s77, 0x2000
	s_add_u32 s78, s88, 0x80080
	v_lshl_add_u64 v[182:183], v[184:185], 0, s[12:13]
	s_addc_u32 s79, s89, 0
	s_add_i32 s77, s80, s0
	global_load_lds_dwordx4 v[182:183], off
	v_lshl_add_u64 v[182:183], s[78:79], 0, v[168:169]
	s_mov_b32 m0, s77
	s_nop 0
	global_load_lds_dwordx4 v[182:183], off
	v_lshl_add_u64 v[182:183], s[78:79], 0, v[172:173]
	s_add_i32 m0, s77, 0x2000
	s_nop 0
	global_load_lds_dwordx4 v[182:183], off
	s_waitcnt vmcnt(6)
	s_waitcnt lgkmcnt(0)
	s_barrier
	s_setprio 1
	s_waitcnt lgkmcnt(0)
	v_mfma_f32_16x16x128_f8f6f4 v[94:97], v[2:9], v[196:203], v[94:97]
	v_mfma_f32_16x16x128_f8f6f4 v[90:93], v[10:17], v[196:203], v[90:93]
	v_mfma_f32_16x16x128_f8f6f4 v[78:81], v[2:9], v[204:211], v[78:81]
	v_mfma_f32_16x16x128_f8f6f4 v[74:77], v[10:17], v[204:211], v[74:77]
	v_mfma_f32_16x16x128_f8f6f4 v[62:65], v[2:9], v[212:219], v[62:65]
	v_lshl_add_u64 v[182:183], v[186:187], 0, s[12:13]
	s_mov_b32 m0, s93
	s_nop 0
	global_load_lds_dwordx4 v[182:183], off
	v_mfma_f32_16x16x128_f8f6f4 v[58:61], v[10:17], v[212:219], v[58:61]
	v_mfma_f32_16x16x128_f8f6f4 v[46:49], v[2:9], v[220:227], v[46:49]
	v_mfma_f32_16x16x128_f8f6f4 v[42:45], v[10:17], v[220:227], v[42:45]
	s_setprio 0
	s_setprio 1
	v_mfma_f32_16x16x128_f8f6f4 v[86:89], v[18:25], v[196:203], v[86:89]
	v_mfma_f32_16x16x128_f8f6f4 v[82:85], v[26:33], v[196:203], v[82:85]
	v_mfma_f32_16x16x128_f8f6f4 v[70:73], v[18:25], v[204:211], v[70:73]
	v_mfma_f32_16x16x128_f8f6f4 v[66:69], v[26:33], v[204:211], v[66:69]
	v_mfma_f32_16x16x128_f8f6f4 v[54:57], v[18:25], v[212:219], v[54:57]
	v_lshl_add_u64 v[182:183], v[188:189], 0, s[12:13]
	s_mov_b32 m0, s94
	s_nop 0
	global_load_lds_dwordx4 v[182:183], off
	v_mfma_f32_16x16x128_f8f6f4 v[50:53], v[26:33], v[212:219], v[50:53]
	v_mfma_f32_16x16x128_f8f6f4 v[38:41], v[18:25], v[220:227], v[38:41]
	v_mfma_f32_16x16x128_f8f6f4 v[34:37], v[26:33], v[220:227], v[34:37]
	s_setprio 0
	s_barrier
	s_add_i32 s76, s76, 2
	s_add_u32 s86, s86, 0x100
	s_addc_u32 s87, s87, 0
	s_add_u32 s74, s74, 0x100
	s_addc_u32 s75, s75, 0
	s_cmp_gt_u32 s76, 29
	s_cbranch_scc0 .LBB0_225
	s_nop 7
	s_nop 7
	s_and_b64 vcc, exec, s[14:15]
	s_cbranch_vccz .LBB0_228
	s_barrier

; #define PG8_STAGE(bufoff, gbase, voff) do { if constexpr (DIAG >= 1) break; _Pragma("unroll") for (int _i = 0; _i < 2; ++_i) \
;         __builtin_amdgcn_global_load_lds((const unsigned*)((const char*)(gbase) + (voff)[_i]), (PG8_LAS unsigned*)(lds + (bufoff) + ldsw + _i * 8192), 16, 0, 0); } while (0)
; #define PG8_LDA(dst, b, h) do { if constexpr (DIAG == 2 || DIAG == 3) break; _Pragma("unroll") for (int m = 0; m < 4; ++m) _Pragma("unroll") for (int k = 0; k < 2; ++k) dst[m][k] = *(const PG8_LAS bf16x8*)(lds + PG8_SA(b, h) + aoff + m * 2048 + k * 1024); } while (0)
; #define PG8_LDB(dst, b, h) do { if constexpr (DIAG == 2 || DIAG == 3) break; _Pragma("unroll") for (int n = 0; n < 2; ++n) _Pragma("unroll") for (int k = 0; k < 2; ++k) dst[n][k] = *(const PG8_LAS bf16x8*)(lds + PG8_SB(b, h) + boff + n * 2048 + k * 1024); } while (0)
; #define PG8_WAIT_V(n) asm volatile("s_waitcnt vmcnt(" #n ")" ::: "memory")
; #define PG8_WAIT_L(n) asm volatile("s_waitcnt lgkmcnt(" #n ")" ::: "memory")
; #define PG8_BAR __builtin_amdgcn_s_barrier()
; #define PG8_LP_ON __builtin_amdgcn_s_setprio(PG8_LOADPRIO)
; #define PG8_LP_OFF __builtin_amdgcn_s_setprio(0)
; #define PG8_LP_ON do {} while (0)
; #define PG8_LP_OFF do {} while (0)
; #define PG8_SCHED __builtin_amdgcn_sched_barrier(0)
;     ...
;             if constexpr (SP2) {
;             PG8_LP_ON; PG8_LDB(B0, 0, 0); PG8_LDB(B1, 0, 1); PG8_SCHED; PG8_LDA(At, 0, 0); PG8_STAGE(PG8_SA(1, 1), a1 + hstep, voffA);
;             PG8_LP_OFF; PG8_WAIT_V(8); PG8_WAIT_L(0); PG8_BAR; PG8_MMA(0, 0, At, B0); PG8_MMA(0, 1, At, B1); PG8_BAR; PG8_SCHED;
;             PG8_LP_ON; PG8_LDA(At, 0, 1); PG8_STAGE(PG8_SB(0, 0), b2, voffB); PG8_STAGE(PG8_SB(0, 1), b2 + hstep, voffB); PG8_STAGE(PG8_SA(0, 0), a2, voffA);
;             PG8_LP_OFF; PG8_WAIT_V(8); PG8_WAIT_L(0); PG8_BAR; PG8_MMA(1, 0, At, B0); PG8_MMA(1, 1, At, B1); PG8_BAR; PG8_SCHED;
.LBB0_306:
	ds_read_b128 v[26:29], v200
	ds_read_b128 v[30:33], v200 offset:1024
	ds_read_b128 v[18:21], v200 offset:2048
	ds_read_b128 v[22:25], v200 offset:3072
	ds_read_b128 v[10:13], v201
	ds_read_b128 v[14:17], v201 offset:1024
	ds_read_b128 v[2:5], v201 offset:2048
	ds_read_b128 v[6:9], v201 offset:3072
	ds_read_b128 v[180:183], v202
	ds_read_b128 v[184:187], v202 offset:1024
	ds_read_b128 v[188:191], v202 offset:2048
	ds_read_b128 v[192:195], v202 offset:3072
	ds_read_b128 v[204:207], v202 offset:4096
	ds_read_b128 v[208:211], v202 offset:5120
	ds_read_b128 v[212:215], v202 offset:6144
	ds_read_b128 v[216:219], v202 offset:7168
	s_add_u32 s74, s4, 0xffea8080
	s_addc_u32 s75, s5, -1
	s_cmpk_eq_i32 s77, 0x52
	s_cselect_b32 s87, s23, s75
	s_cselect_b32 s86, s22, s74
	s_cselect_b32 s75, s73, s76
	s_cselect_b32 s74, s72, s27
	v_lshl_add_u64 v[196:197], s[4:5], 0, v[172:173]
	s_add_i32 m0, s84, 0xc000
	s_nop 0
	global_load_lds_dwordx4 v[196:197], off
	v_lshl_add_u64 v[196:197], s[4:5], 0, v[174:175]
	s_add_i32 m0, s84, 0xe000
	s_nop 0
	global_load_lds_dwordx4 v[196:197], off
	s_waitcnt vmcnt(8)
	s_waitcnt lgkmcnt(0)
	s_barrier
	s_setprio 1
	s_waitcnt lgkmcnt(0)
	v_mfma_f32_16x16x128_f8f6f4 v[158:161], v[26:33], v[180:187], v[158:161]
	v_mfma_f32_16x16x128_f8f6f4 v[154:157], v[18:25], v[180:187], v[154:157]
	v_mfma_f32_16x16x128_f8f6f4 v[142:145], v[26:33], v[188:195], v[142:145]
	v_mfma_f32_16x16x128_f8f6f4 v[138:141], v[18:25], v[188:195], v[138:141]
	v_mfma_f32_16x16x128_f8f6f4 v[126:129], v[26:33], v[204:211], v[126:129]
	v_mfma_f32_16x16x128_f8f6f4 v[122:125], v[18:25], v[204:211], v[122:125]
	v_mfma_f32_16x16x128_f8f6f4 v[110:113], v[26:33], v[212:219], v[110:113]
	v_mfma_f32_16x16x128_f8f6f4 v[106:109], v[18:25], v[212:219], v[106:109]
	s_setprio 0
	s_setprio 1
	v_mfma_f32_16x16x128_f8f6f4 v[150:153], v[10:17], v[180:187], v[150:153]
	v_mfma_f32_16x16x128_f8f6f4 v[146:149], v[2:9], v[180:187], v[146:149]
	v_mfma_f32_16x16x128_f8f6f4 v[134:137], v[10:17], v[188:195], v[134:137]
	v_mfma_f32_16x16x128_f8f6f4 v[130:133], v[2:9], v[188:195], v[130:133]
	v_mfma_f32_16x16x128_f8f6f4 v[118:121], v[10:17], v[204:211], v[118:121]
	v_mfma_f32_16x16x128_f8f6f4 v[114:117], v[2:9], v[204:211], v[114:117]
	v_mfma_f32_16x16x128_f8f6f4 v[102:105], v[10:17], v[212:219], v[102:105]
	v_mfma_f32_16x16x128_f8f6f4 v[98:101], v[2:9], v[212:219], v[98:101]
	s_setprio 0
	s_barrier
	ds_read_b128 v[188:191], v202 offset:16384
	ds_read_b128 v[192:195], v202 offset:17408
	ds_read_b128 v[204:207], v202 offset:18432
	ds_read_b128 v[208:211], v202 offset:19456
	ds_read_b128 v[212:215], v202 offset:20480
	ds_read_b128 v[216:219], v202 offset:21504
	ds_read_b128 v[220:223], v202 offset:22528
	ds_read_b128 v[224:227], v202 offset:23552
	s_add_i32 s78, s96, s21
	v_lshl_add_u64 v[180:181], s[74:75], 0, v[166:167]
	s_mov_b32 m0, s78
	s_nop 0
	global_load_lds_dwordx4 v[180:181], off
	s_add_i32 m0, s78, 0x2000
	s_add_u32 s78, s74, 0x158000
	v_lshl_add_u64 v[182:183], s[74:75], 0, v[168:169]
	s_addc_u32 s79, s75, 0
	s_add_i32 s80, s97, s21
	global_load_lds_dwordx4 v[182:183], off
	v_lshl_add_u64 v[184:185], s[78:79], 0, v[166:167]
	s_mov_b32 m0, s80
	v_lshl_add_u64 v[186:187], s[86:87], 0, v[168:169]
	global_load_lds_dwordx4 v[184:185], off
	v_lshl_add_u64 v[184:185], s[78:79], 0, v[168:169]
	s_add_i32 m0, s80, 0x2000
	s_nop 0
	global_load_lds_dwordx4 v[184:185], off
	s_waitcnt vmcnt(6)
	s_waitcnt lgkmcnt(0)
	s_barrier
	s_setprio 1
	s_waitcnt lgkmcnt(0)
	v_mfma_f32_16x16x128_f8f6f4 v[94:97], v[26:33], v[188:195], v[94:97]
	v_mfma_f32_16x16x128_f8f6f4 v[90:93], v[18:25], v[188:195], v[90:93]
	v_mfma_f32_16x16x128_f8f6f4 v[78:81], v[26:33], v[204:211], v[78:81]
	v_mfma_f32_16x16x128_f8f6f4 v[74:77], v[18:25], v[204:211], v[74:77]
	v_mfma_f32_16x16x128_f8f6f4 v[62:65], v[26:33], v[212:219], v[62:65]
	v_lshl_add_u64 v[184:185], s[86:87], 0, v[166:167]
	s_mov_b32 m0, s84
	s_nop 0
	global_load_lds_dwordx4 v[184:185], off
	v_mfma_f32_16x16x128_f8f6f4 v[58:61], v[18:25], v[212:219], v[58:61]
	v_mfma_f32_16x16x128_f8f6f4 v[46:49], v[26:33], v[220:227], v[46:49]
	v_mfma_f32_16x16x128_f8f6f4 v[42:45], v[18:25], v[220:227], v[42:45]
	s_setprio 0
	s_setprio 1
	v_mfma_f32_16x16x128_f8f6f4 v[86:89], v[10:17], v[188:195], v[86:89]
	v_mfma_f32_16x16x128_f8f6f4 v[82:85], v[2:9], v[188:195], v[82:85]
	v_mfma_f32_16x16x128_f8f6f4 v[70:73], v[10:17], v[204:211], v[70:73]
	v_mfma_f32_16x16x128_f8f6f4 v[66:69], v[2:9], v[204:211], v[66:69]
	v_mfma_f32_16x16x128_f8f6f4 v[54:57], v[10:17], v[212:219], v[54:57]
	s_mov_b32 m0, s85
	s_nop 0
	global_load_lds_dwordx4 v[186:187], off
	v_mfma_f32_16x16x128_f8f6f4 v[50:53], v[2:9], v[212:219], v[50:53]
	v_mfma_f32_16x16x128_f8f6f4 v[38:41], v[10:17], v[220:227], v[38:41]
	v_mfma_f32_16x16x128_f8f6f4 v[34:37], v[2:9], v[220:227], v[34:37]
	s_setprio 0
	s_barrier
; #define PG8_STAGE(bufoff, gbase, voff) do { if constexpr (DIAG >= 1) break; _Pragma("unroll") for (int _i = 0; _i < 2; ++_i) \
;         __builtin_amdgcn_global_load_lds((const unsigned*)((const char*)(gbase) + (voff)[_i]), (PG8_LAS unsigned*)(lds + (bufoff) + ldsw + _i * 8192), 16, 0, 0); } while (0)
; #define PG8_LDA(dst, b, h) do { if constexpr (DIAG == 2 || DIAG == 3) break; _Pragma("unroll") for (int m = 0; m < 4; ++m) _Pragma("unroll") for (int k = 0; k < 2; ++k) dst[m][k] = *(const PG8_LAS bf16x8*)(lds + PG8_SA(b, h) + aoff + m * 2048 + k * 1024); } while (0)
; #define PG8_LDB(dst, b, h) do { if constexpr (DIAG == 2 || DIAG == 3) break; _Pragma("unroll") for (int n = 0; n < 2; ++n) _Pragma("unroll") for (int k = 0; k < 2; ++k) dst[n][k] = *(const PG8_LAS bf16x8*)(lds + PG8_SB(b, h) + boff + n * 2048 + k * 1024); } while (0)
; #define PG8_WAIT_V(n) asm volatile("s_waitcnt vmcnt(" #n ")" ::: "memory")
; #define PG8_WAIT_L(n) asm volatile("s_waitcnt lgkmcnt(" #n ")" ::: "memory")
; #define PG8_BAR __builtin_amdgcn_s_barrier()
; #define PG8_LP_ON __builtin_amdgcn_s_setprio(PG8_LOADPRIO)
; #define PG8_LP_OFF __builtin_amdgcn_s_setprio(0)
; #define PG8_LP_ON do {} while (0)
; #define PG8_LP_OFF do {} while (0)
; #define PG8_SCHED __builtin_amdgcn_sched_barrier(0)
;     ...
;             PG8_LP_ON; PG8_LDB(B0, 1, 0); PG8_LDB(B1, 1, 1); PG8_SCHED; PG8_LDA(At, 1, 0); PG8_STAGE(PG8_SA(0, 1), a2 + hstep, voffA);
;             PG8_LP_OFF; PG8_WAIT_V(8); PG8_WAIT_L(0); PG8_BAR; PG8_MMA(0, 0, At, B0); PG8_MMA(0, 1, At, B1); PG8_BAR; PG8_SCHED;
;             PG8_LP_ON; PG8_LDA(At, 1, 1); PG8_STAGE(PG8_SB(1, 0), b3, voffB); PG8_STAGE(PG8_SB(1, 1), b3 + hstep, voffB); PG8_STAGE(PG8_SA(1, 0), a3, voffA);
;             PG8_LP_OFF; PG8_WAIT_V(8); PG8_WAIT_L(0); PG8_BAR; PG8_MMA(1, 0, At, B0); PG8_MMA(1, 1, At, B1); PG8_BAR; PG8_SCHED;
	s_add_i32 s80, 0, 0x18000
	s_add_i32 s81, 0, 0x1c000
	v_add_u32_e32 v14, s80, v198
	v_add_u32_e32 v30, s81, v198
	ds_read_b128 v[2:5], v14
	ds_read_b128 v[6:9], v14 offset:1024
	ds_read_b128 v[10:13], v14 offset:2048
	ds_read_b128 v[14:17], v14 offset:3072
	ds_read_b128 v[18:21], v30
	ds_read_b128 v[22:25], v30 offset:1024
	ds_read_b128 v[26:29], v30 offset:2048
	ds_read_b128 v[30:33], v30 offset:3072
	ds_read_b128 v[188:191], v202 offset:32768
	ds_read_b128 v[192:195], v202 offset:33792
	ds_read_b128 v[204:207], v202 offset:34816
	ds_read_b128 v[208:211], v202 offset:35840
	ds_read_b128 v[212:215], v202 offset:36864
	ds_read_b128 v[216:219], v202 offset:37888
	ds_read_b128 v[220:223], v202 offset:38912
	ds_read_b128 v[224:227], v202 offset:39936
	s_add_u32 s78, s86, 0x158000
	s_addc_u32 s79, s87, 0
	s_mov_b32 m0, s88
	v_lshl_add_u64 v[196:197], s[78:79], 0, v[166:167]
	global_load_lds_dwordx4 v[196:197], off
	v_lshl_add_u64 v[196:197], s[78:79], 0, v[168:169]
	s_mov_b32 m0, s89
	s_nop 0
	global_load_lds_dwordx4 v[196:197], off
	s_waitcnt vmcnt(8)
	s_waitcnt lgkmcnt(0)
	s_barrier
	s_setprio 1
	s_waitcnt lgkmcnt(0)
	v_mfma_f32_16x16x128_f8f6f4 v[158:161], v[2:9], v[188:195], v[158:161]
	v_mfma_f32_16x16x128_f8f6f4 v[154:157], v[10:17], v[188:195], v[154:157]
	v_mfma_f32_16x16x128_f8f6f4 v[142:145], v[2:9], v[204:211], v[142:145]
	v_mfma_f32_16x16x128_f8f6f4 v[138:141], v[10:17], v[204:211], v[138:141]
	v_mfma_f32_16x16x128_f8f6f4 v[126:129], v[2:9], v[212:219], v[126:129]
	v_mfma_f32_16x16x128_f8f6f4 v[122:125], v[10:17], v[212:219], v[122:125]
	v_mfma_f32_16x16x128_f8f6f4 v[110:113], v[2:9], v[220:227], v[110:113]
	v_mfma_f32_16x16x128_f8f6f4 v[106:109], v[10:17], v[220:227], v[106:109]
	s_setprio 0
	s_setprio 1
	v_mfma_f32_16x16x128_f8f6f4 v[150:153], v[18:25], v[188:195], v[150:153]
	v_mfma_f32_16x16x128_f8f6f4 v[146:149], v[26:33], v[188:195], v[146:149]
	v_mfma_f32_16x16x128_f8f6f4 v[134:137], v[18:25], v[204:211], v[134:137]
	v_mfma_f32_16x16x128_f8f6f4 v[130:133], v[26:33], v[204:211], v[130:133]
	v_mfma_f32_16x16x128_f8f6f4 v[118:121], v[18:25], v[212:219], v[118:121]
	v_mfma_f32_16x16x128_f8f6f4 v[114:117], v[26:33], v[212:219], v[114:117]
	v_mfma_f32_16x16x128_f8f6f4 v[102:105], v[18:25], v[220:227], v[102:105]
	v_mfma_f32_16x16x128_f8f6f4 v[98:101], v[26:33], v[220:227], v[98:101]
	s_setprio 0
	s_barrier
	ds_read_b128 v[188:191], v202 offset:49152
	ds_read_b128 v[192:195], v202 offset:50176
	ds_read_b128 v[204:207], v202 offset:51200
	ds_read_b128 v[208:211], v202 offset:52224
	ds_read_b128 v[212:215], v202 offset:53248
	ds_read_b128 v[216:219], v202 offset:54272
	ds_read_b128 v[220:223], v202 offset:55296
	ds_read_b128 v[224:227], v202 offset:56320
	s_add_i32 s78, s80, s21
	v_lshl_add_u64 v[180:181], v[180:181], 0, s[14:15]
	s_mov_b32 m0, s78
	s_nop 0
	global_load_lds_dwordx4 v[180:181], off
	s_add_i32 m0, s78, 0x2000
	s_add_u32 s74, s74, 0x158080
	v_lshl_add_u64 v[180:181], v[182:183], 0, s[14:15]
	s_addc_u32 s75, s75, 0
	s_add_i32 s78, s81, s21
	global_load_lds_dwordx4 v[180:181], off
	v_lshl_add_u64 v[180:181], s[74:75], 0, v[166:167]
	s_mov_b32 m0, s78
	s_nop 0
	global_load_lds_dwordx4 v[180:181], off
	v_lshl_add_u64 v[180:181], s[74:75], 0, v[168:169]
	s_add_i32 m0, s78, 0x2000
	s_nop 0
	global_load_lds_dwordx4 v[180:181], off
	s_waitcnt vmcnt(6)
	s_waitcnt lgkmcnt(0)
	s_barrier
	s_setprio 1
	s_waitcnt lgkmcnt(0)
	v_mfma_f32_16x16x128_f8f6f4 v[94:97], v[2:9], v[188:195], v[94:97]
	v_mfma_f32_16x16x128_f8f6f4 v[90:93], v[10:17], v[188:195], v[90:93]
	v_mfma_f32_16x16x128_f8f6f4 v[78:81], v[2:9], v[204:211], v[78:81]
	v_mfma_f32_16x16x128_f8f6f4 v[74:77], v[10:17], v[204:211], v[74:77]
	v_mfma_f32_16x16x128_f8f6f4 v[62:65], v[2:9], v[212:219], v[62:65]
	v_lshl_add_u64 v[180:181], v[184:185], 0, s[14:15]
	s_mov_b32 m0, s94
	s_nop 0
	global_load_lds_dwordx4 v[180:181], off
	v_mfma_f32_16x16x128_f8f6f4 v[58:61], v[10:17], v[212:219], v[58:61]
	v_mfma_f32_16x16x128_f8f6f4 v[46:49], v[2:9], v[220:227], v[46:49]
	v_mfma_f32_16x16x128_f8f6f4 v[42:45], v[10:17], v[220:227], v[42:45]
	s_setprio 0
	s_setprio 1
	v_mfma_f32_16x16x128_f8f6f4 v[86:89], v[18:25], v[188:195], v[86:89]
	v_mfma_f32_16x16x128_f8f6f4 v[82:85], v[26:33], v[188:195], v[82:85]
	v_mfma_f32_16x16x128_f8f6f4 v[70:73], v[18:25], v[204:211], v[70:73]
	v_mfma_f32_16x16x128_f8f6f4 v[66:69], v[26:33], v[204:211], v[66:69]
	v_mfma_f32_16x16x128_f8f6f4 v[54:57], v[18:25], v[212:219], v[54:57]
	v_lshl_add_u64 v[180:181], v[186:187], 0, s[14:15]
	s_mov_b32 m0, s95
	s_nop 0
	global_load_lds_dwordx4 v[180:181], off
	v_mfma_f32_16x16x128_f8f6f4 v[50:53], v[26:33], v[212:219], v[50:53]
	v_mfma_f32_16x16x128_f8f6f4 v[38:41], v[18:25], v[220:227], v[38:41]
	v_mfma_f32_16x16x128_f8f6f4 v[34:37], v[26:33], v[220:227], v[34:37]
	s_setprio 0
	s_barrier
	s_add_i32 s77, s77, 2
	s_add_u32 s4, s4, 0x100
	s_addc_u32 s5, s5, 0
	s_add_u32 s27, s27, 0x100
	s_addc_u32 s76, s76, 0
	s_cmpk_gt_u32 s77, 0x53
	s_cbranch_scc0 .LBB0_306
	s_nop 7
	s_nop 7
	s_and_b64 vcc, exec, s[16:17]
	s_cbranch_vccz .LBB0_309
	s_barrier

; #define PG8_STAGE(bufoff, gbase, voff) do { if constexpr (DIAG >= 1) break; _Pragma("unroll") for (int _i = 0; _i < 2; ++_i) \
;         __builtin_amdgcn_global_load_lds((const unsigned*)((const char*)(gbase) + (voff)[_i]), (PG8_LAS unsigned*)(lds + (bufoff) + ldsw + _i * 8192), 16, 0, 0); } while (0)
; #define PG8_LDA(dst, b, h) do { if constexpr (DIAG == 2 || DIAG == 3) break; _Pragma("unroll") for (int m = 0; m < 4; ++m) _Pragma("unroll") for (int k = 0; k < 2; ++k) dst[m][k] = *(const PG8_LAS bf16x8*)(lds + PG8_SA(b, h) + aoff + m * 2048 + k * 1024); } while (0)
; #define PG8_LDB(dst, b, h) do { if constexpr (DIAG == 2 || DIAG == 3) break; _Pragma("unroll") for (int n = 0; n < 2; ++n) _Pragma("unroll") for (int k = 0; k < 2; ++k) dst[n][k] = *(const PG8_LAS bf16x8*)(lds + PG8_SB(b, h) + boff + n * 2048 + k * 1024); } while (0)
; #define PG8_WAIT_V(n) asm volatile("s_waitcnt vmcnt(" #n ")" ::: "memory")
; #define PG8_WAIT_L(n) asm volatile("s_waitcnt lgkmcnt(" #n ")" ::: "memory")
; #define PG8_BAR __builtin_amdgcn_s_barrier()
; #define PG8_LP_ON __builtin_amdgcn_s_setprio(PG8_LOADPRIO)
; #define PG8_LP_OFF __builtin_amdgcn_s_setprio(0)
; #define PG8_LP_ON do {} while (0)
; #define PG8_LP_OFF do {} while (0)
; #define PG8_SCHED __builtin_amdgcn_sched_barrier(0)
;     ...
;             if constexpr (SP2) {
;             PG8_LP_ON; PG8_LDB(B0, 0, 0); PG8_LDB(B1, 0, 1); PG8_SCHED; PG8_LDA(At, 0, 0); PG8_STAGE(PG8_SA(1, 1), a1 + hstep, voffA);
;             PG8_LP_OFF; PG8_WAIT_V(8); PG8_WAIT_L(0); PG8_BAR; PG8_MMA(0, 0, At, B0); PG8_MMA(0, 1, At, B1); PG8_BAR; PG8_SCHED;
;             PG8_LP_ON; PG8_LDA(At, 0, 1); PG8_STAGE(PG8_SB(0, 0), b2, voffB); PG8_STAGE(PG8_SB(0, 1), b2 + hstep, voffB); PG8_STAGE(PG8_SA(0, 0), a2, voffA);
;             PG8_LP_OFF; PG8_WAIT_V(8); PG8_WAIT_L(0); PG8_BAR; PG8_MMA(1, 0, At, B0); PG8_MMA(1, 1, At, B1); PG8_BAR; PG8_SCHED;
.LBB0_505:
	ds_read_b128 v[26:29], v205
	ds_read_b128 v[30:33], v205 offset:1024
	ds_read_b128 v[18:21], v205 offset:2048
	ds_read_b128 v[22:25], v205 offset:3072
	ds_read_b128 v[10:13], v206
	ds_read_b128 v[14:17], v206 offset:1024
	ds_read_b128 v[2:5], v206 offset:2048
	ds_read_b128 v[6:9], v206 offset:3072
	ds_read_b128 v[182:185], v207
	ds_read_b128 v[186:189], v207 offset:1024
	ds_read_b128 v[208:211], v207 offset:2048
	ds_read_b128 v[212:215], v207 offset:3072
	ds_read_b128 v[216:219], v207 offset:4096
	ds_read_b128 v[220:223], v207 offset:5120
	ds_read_b128 v[224:227], v207 offset:6144
	ds_read_b128 v[228:231], v207 offset:7168
	s_add_u32 s76, s74, 0xfff80080
	s_addc_u32 s77, s75, -1
	s_cmp_eq_u32 s82, 28
	s_cselect_b32 s79, s19, s77
	s_cselect_b32 s78, s95, s76
	s_cselect_b32 s77, s17, s81
	s_cselect_b32 s76, s96, s80
	v_lshl_add_u64 v[232:233], s[74:75], 0, v[174:175]
	s_add_i32 m0, s55, 0xc000
	s_nop 0
	global_load_lds_dwordx4 v[232:233], off
	v_lshl_add_u64 v[232:233], s[74:75], 0, v[176:177]
	s_add_i32 m0, s55, 0xe000
	s_nop 0
	global_load_lds_dwordx4 v[232:233], off
	s_waitcnt vmcnt(8)
	s_waitcnt lgkmcnt(0)
	s_barrier
	s_setprio 1
	s_waitcnt lgkmcnt(0)
	v_mfma_f32_16x16x128_f8f6f4 v[158:161], v[26:33], v[182:189], v[158:161]
	v_mfma_f32_16x16x128_f8f6f4 v[154:157], v[18:25], v[182:189], v[154:157]
	v_mfma_f32_16x16x128_f8f6f4 v[146:149], v[26:33], v[208:215], v[146:149]
	v_mfma_f32_16x16x128_f8f6f4 v[138:141], v[18:25], v[208:215], v[138:141]
	v_mfma_f32_16x16x128_f8f6f4 v[130:133], v[26:33], v[216:223], v[130:133]
	v_mfma_f32_16x16x128_f8f6f4 v[122:125], v[18:25], v[216:223], v[122:125]
	v_mfma_f32_16x16x128_f8f6f4 v[114:117], v[26:33], v[224:231], v[114:117]
	v_mfma_f32_16x16x128_f8f6f4 v[106:109], v[18:25], v[224:231], v[106:109]
	s_setprio 0
	s_setprio 1
	v_mfma_f32_16x16x128_f8f6f4 v[150:153], v[10:17], v[182:189], v[150:153]
	v_mfma_f32_16x16x128_f8f6f4 v[142:145], v[2:9], v[182:189], v[142:145]
	v_mfma_f32_16x16x128_f8f6f4 v[134:137], v[10:17], v[208:215], v[134:137]
	v_mfma_f32_16x16x128_f8f6f4 v[126:129], v[2:9], v[208:215], v[126:129]
	v_mfma_f32_16x16x128_f8f6f4 v[118:121], v[10:17], v[216:223], v[118:121]
	v_mfma_f32_16x16x128_f8f6f4 v[110:113], v[2:9], v[216:223], v[110:113]
	v_mfma_f32_16x16x128_f8f6f4 v[102:105], v[10:17], v[224:231], v[102:105]
	v_mfma_f32_16x16x128_f8f6f4 v[98:101], v[2:9], v[224:231], v[98:101]
	s_setprio 0
	s_barrier
	ds_read_b128 v[208:211], v207 offset:16384
	ds_read_b128 v[212:215], v207 offset:17408
	ds_read_b128 v[216:219], v207 offset:18432
	ds_read_b128 v[220:223], v207 offset:19456
	ds_read_b128 v[224:227], v207 offset:20480
	ds_read_b128 v[228:231], v207 offset:21504
	ds_read_b128 v[232:235], v207 offset:22528
	ds_read_b128 v[236:239], v207 offset:23552
	s_add_i32 s83, s92, s86
	v_lshl_add_u64 v[182:183], s[76:77], 0, v[168:169]
	s_mov_b32 m0, s83
	s_nop 0
	global_load_lds_dwordx4 v[182:183], off
	s_add_i32 m0, s83, 0x2000
	s_add_u32 vcc_lo, s76, 0x80000
	v_lshl_add_u64 v[184:185], s[76:77], 0, v[172:173]
	s_addc_u32 vcc_hi, s77, 0
	s_add_i32 s83, s93, s86
	global_load_lds_dwordx4 v[184:185], off
	v_lshl_add_u64 v[186:187], vcc, 0, v[168:169]
	s_mov_b32 m0, s83
	v_lshl_add_u64 v[188:189], s[78:79], 0, v[170:171]
	global_load_lds_dwordx4 v[186:187], off
	v_lshl_add_u64 v[186:187], vcc, 0, v[172:173]
	s_add_i32 m0, s83, 0x2000
	s_nop 0
	global_load_lds_dwordx4 v[186:187], off
	s_waitcnt vmcnt(6)
	s_waitcnt lgkmcnt(0)
	s_barrier
	s_setprio 1
	s_waitcnt lgkmcnt(0)
	v_mfma_f32_16x16x128_f8f6f4 v[94:97], v[26:33], v[208:215], v[94:97]
	v_mfma_f32_16x16x128_f8f6f4 v[90:93], v[18:25], v[208:215], v[90:93]
	v_mfma_f32_16x16x128_f8f6f4 v[82:85], v[26:33], v[216:223], v[82:85]
	v_mfma_f32_16x16x128_f8f6f4 v[74:77], v[18:25], v[216:223], v[74:77]
	v_mfma_f32_16x16x128_f8f6f4 v[66:69], v[26:33], v[224:231], v[66:69]
	v_lshl_add_u64 v[186:187], s[78:79], 0, v[166:167]
	s_mov_b32 m0, s55
	s_nop 0
	global_load_lds_dwordx4 v[186:187], off
	v_mfma_f32_16x16x128_f8f6f4 v[58:61], v[18:25], v[224:231], v[58:61]
	v_mfma_f32_16x16x128_f8f6f4 v[50:53], v[26:33], v[232:239], v[50:53]
	v_mfma_f32_16x16x128_f8f6f4 v[42:45], v[18:25], v[232:239], v[42:45]
	s_setprio 0
	s_setprio 1
	v_mfma_f32_16x16x128_f8f6f4 v[86:89], v[10:17], v[208:215], v[86:89]
	v_mfma_f32_16x16x128_f8f6f4 v[78:81], v[2:9], v[208:215], v[78:81]
	v_mfma_f32_16x16x128_f8f6f4 v[70:73], v[10:17], v[216:223], v[70:73]
	v_mfma_f32_16x16x128_f8f6f4 v[62:65], v[2:9], v[216:223], v[62:65]
	v_mfma_f32_16x16x128_f8f6f4 v[54:57], v[10:17], v[224:231], v[54:57]
	s_mov_b32 m0, s73
	s_nop 0
	global_load_lds_dwordx4 v[188:189], off
	v_mfma_f32_16x16x128_f8f6f4 v[46:49], v[2:9], v[224:231], v[46:49]
	v_mfma_f32_16x16x128_f8f6f4 v[38:41], v[10:17], v[232:239], v[38:41]
	v_mfma_f32_16x16x128_f8f6f4 v[34:37], v[2:9], v[232:239], v[34:37]
	s_setprio 0
	s_barrier
; #define PG8_STAGE(bufoff, gbase, voff) do { if constexpr (DIAG >= 1) break; _Pragma("unroll") for (int _i = 0; _i < 2; ++_i) \
;         __builtin_amdgcn_global_load_lds((const unsigned*)((const char*)(gbase) + (voff)[_i]), (PG8_LAS unsigned*)(lds + (bufoff) + ldsw + _i * 8192), 16, 0, 0); } while (0)
; #define PG8_LDA(dst, b, h) do { if constexpr (DIAG == 2 || DIAG == 3) break; _Pragma("unroll") for (int m = 0; m < 4; ++m) _Pragma("unroll") for (int k = 0; k < 2; ++k) dst[m][k] = *(const PG8_LAS bf16x8*)(lds + PG8_SA(b, h) + aoff + m * 2048 + k * 1024); } while (0)
; #define PG8_LDB(dst, b, h) do { if constexpr (DIAG == 2 || DIAG == 3) break; _Pragma("unroll") for (int n = 0; n < 2; ++n) _Pragma("unroll") for (int k = 0; k < 2; ++k) dst[n][k] = *(const PG8_LAS bf16x8*)(lds + PG8_SB(b, h) + boff + n * 2048 + k * 1024); } while (0)
; #define PG8_WAIT_V(n) asm volatile("s_waitcnt vmcnt(" #n ")" ::: "memory")
; #define PG8_WAIT_L(n) asm volatile("s_waitcnt lgkmcnt(" #n ")" ::: "memory")
; #define PG8_BAR __builtin_amdgcn_s_barrier()
; #define PG8_LP_ON __builtin_amdgcn_s_setprio(PG8_LOADPRIO)
; #define PG8_LP_OFF __builtin_amdgcn_s_setprio(0)
; #define PG8_LP_ON do {} while (0)
; #define PG8_LP_OFF do {} while (0)
; #define PG8_SCHED __builtin_amdgcn_sched_barrier(0)
;     ...
;             PG8_LP_ON; PG8_LDB(B0, 1, 0); PG8_LDB(B1, 1, 1); PG8_SCHED; PG8_LDA(At, 1, 0); PG8_STAGE(PG8_SA(0, 1), a2 + hstep, voffA);
;             PG8_LP_OFF; PG8_WAIT_V(8); PG8_WAIT_L(0); PG8_BAR; PG8_MMA(0, 0, At, B0); PG8_MMA(0, 1, At, B1); PG8_BAR; PG8_SCHED;
;             PG8_LP_ON; PG8_LDA(At, 1, 1); PG8_STAGE(PG8_SB(1, 0), b3, voffB); PG8_STAGE(PG8_SB(1, 1), b3 + hstep, voffB); PG8_STAGE(PG8_SA(1, 0), a3, voffA);
;             PG8_LP_OFF; PG8_WAIT_V(8); PG8_WAIT_L(0); PG8_BAR; PG8_MMA(1, 0, At, B0); PG8_MMA(1, 1, At, B1); PG8_BAR; PG8_SCHED;
	s_add_i32 s83, 0, 0x18000
	s_add_i32 s97, 0, 0x1c000
	v_add_u32_e32 v14, s83, v203
	v_add_u32_e32 v30, s97, v203
	ds_read_b128 v[2:5], v14
	ds_read_b128 v[6:9], v14 offset:1024
	ds_read_b128 v[10:13], v14 offset:2048
	ds_read_b128 v[14:17], v14 offset:3072
	ds_read_b128 v[18:21], v30
	ds_read_b128 v[22:25], v30 offset:1024
	ds_read_b128 v[26:29], v30 offset:2048
	ds_read_b128 v[30:33], v30 offset:3072
	ds_read_b128 v[208:211], v207 offset:32768
	ds_read_b128 v[212:215], v207 offset:33792
	ds_read_b128 v[216:219], v207 offset:34816
	ds_read_b128 v[220:223], v207 offset:35840
	ds_read_b128 v[224:227], v207 offset:36864
	ds_read_b128 v[228:231], v207 offset:37888
	ds_read_b128 v[232:235], v207 offset:38912
	ds_read_b128 v[236:239], v207 offset:39936
	s_add_u32 s78, s78, 0x80000
	s_addc_u32 s79, s79, 0
	s_mov_b32 m0, s87
	v_lshl_add_u64 v[240:241], s[78:79], 0, v[166:167]
	global_load_lds_dwordx4 v[240:241], off
	v_lshl_add_u64 v[240:241], s[78:79], 0, v[170:171]
	s_mov_b32 m0, s88
	s_nop 0
	global_load_lds_dwordx4 v[240:241], off
	s_waitcnt vmcnt(8)
	s_waitcnt lgkmcnt(0)
	s_barrier
	s_setprio 1
	s_waitcnt lgkmcnt(0)
	v_mfma_f32_16x16x128_f8f6f4 v[158:161], v[2:9], v[208:215], v[158:161]
	v_mfma_f32_16x16x128_f8f6f4 v[154:157], v[10:17], v[208:215], v[154:157]
	v_mfma_f32_16x16x128_f8f6f4 v[146:149], v[2:9], v[216:223], v[146:149]
	v_mfma_f32_16x16x128_f8f6f4 v[138:141], v[10:17], v[216:223], v[138:141]
	v_mfma_f32_16x16x128_f8f6f4 v[130:133], v[2:9], v[224:231], v[130:133]
	v_mfma_f32_16x16x128_f8f6f4 v[122:125], v[10:17], v[224:231], v[122:125]
	v_mfma_f32_16x16x128_f8f6f4 v[114:117], v[2:9], v[232:239], v[114:117]
	v_mfma_f32_16x16x128_f8f6f4 v[106:109], v[10:17], v[232:239], v[106:109]
	s_setprio 0
	s_setprio 1
	v_mfma_f32_16x16x128_f8f6f4 v[150:153], v[18:25], v[208:215], v[150:153]
	v_mfma_f32_16x16x128_f8f6f4 v[142:145], v[26:33], v[208:215], v[142:145]
	v_mfma_f32_16x16x128_f8f6f4 v[134:137], v[18:25], v[216:223], v[134:137]
	v_mfma_f32_16x16x128_f8f6f4 v[126:129], v[26:33], v[216:223], v[126:129]
	v_mfma_f32_16x16x128_f8f6f4 v[118:121], v[18:25], v[224:231], v[118:121]
	v_mfma_f32_16x16x128_f8f6f4 v[110:113], v[26:33], v[224:231], v[110:113]
	v_mfma_f32_16x16x128_f8f6f4 v[102:105], v[18:25], v[232:239], v[102:105]
	v_mfma_f32_16x16x128_f8f6f4 v[98:101], v[26:33], v[232:239], v[98:101]
	s_setprio 0
	s_barrier
	ds_read_b128 v[208:211], v207 offset:49152
	ds_read_b128 v[212:215], v207 offset:50176
	ds_read_b128 v[216:219], v207 offset:51200
	ds_read_b128 v[220:223], v207 offset:52224
	ds_read_b128 v[224:227], v207 offset:53248
	ds_read_b128 v[228:231], v207 offset:54272
	ds_read_b128 v[232:235], v207 offset:55296
	ds_read_b128 v[236:239], v207 offset:56320
	s_add_i32 s78, s83, s86
	v_lshl_add_u64 v[182:183], v[182:183], 0, s[10:11]
	s_mov_b32 m0, s78
	s_nop 0
	global_load_lds_dwordx4 v[182:183], off
	s_add_i32 m0, s78, 0x2000
	s_add_u32 s76, s76, 0x80080
	v_lshl_add_u64 v[182:183], v[184:185], 0, s[10:11]
	s_addc_u32 s77, s77, 0
	s_add_i32 s78, s97, s86
	global_load_lds_dwordx4 v[182:183], off
	v_lshl_add_u64 v[182:183], s[76:77], 0, v[168:169]
	s_mov_b32 m0, s78
	s_nop 0
	global_load_lds_dwordx4 v[182:183], off
	v_lshl_add_u64 v[182:183], s[76:77], 0, v[172:173]
	s_add_i32 m0, s78, 0x2000
	s_nop 0
	global_load_lds_dwordx4 v[182:183], off
	s_waitcnt vmcnt(6)
	s_waitcnt lgkmcnt(0)
	s_barrier
	s_setprio 1
	s_waitcnt lgkmcnt(0)
	v_mfma_f32_16x16x128_f8f6f4 v[94:97], v[2:9], v[208:215], v[94:97]
	v_mfma_f32_16x16x128_f8f6f4 v[90:93], v[10:17], v[208:215], v[90:93]
	v_mfma_f32_16x16x128_f8f6f4 v[82:85], v[2:9], v[216:223], v[82:85]
	v_mfma_f32_16x16x128_f8f6f4 v[74:77], v[10:17], v[216:223], v[74:77]
	v_mfma_f32_16x16x128_f8f6f4 v[66:69], v[2:9], v[224:231], v[66:69]
	v_lshl_add_u64 v[182:183], v[186:187], 0, s[10:11]
	s_mov_b32 m0, s89
	s_nop 0
	global_load_lds_dwordx4 v[182:183], off
	v_mfma_f32_16x16x128_f8f6f4 v[58:61], v[10:17], v[224:231], v[58:61]
	v_mfma_f32_16x16x128_f8f6f4 v[50:53], v[2:9], v[232:239], v[50:53]
	v_mfma_f32_16x16x128_f8f6f4 v[42:45], v[10:17], v[232:239], v[42:45]
	s_setprio 0
	s_setprio 1
	v_mfma_f32_16x16x128_f8f6f4 v[86:89], v[18:25], v[208:215], v[86:89]
	v_mfma_f32_16x16x128_f8f6f4 v[78:81], v[26:33], v[208:215], v[78:81]
	v_mfma_f32_16x16x128_f8f6f4 v[70:73], v[18:25], v[216:223], v[70:73]
	v_mfma_f32_16x16x128_f8f6f4 v[62:65], v[26:33], v[216:223], v[62:65]
	v_mfma_f32_16x16x128_f8f6f4 v[54:57], v[18:25], v[224:231], v[54:57]
	v_lshl_add_u64 v[182:183], v[188:189], 0, s[10:11]
	s_mov_b32 m0, s90
	s_nop 0
	global_load_lds_dwordx4 v[182:183], off
	v_mfma_f32_16x16x128_f8f6f4 v[46:49], v[26:33], v[224:231], v[46:49]
	v_mfma_f32_16x16x128_f8f6f4 v[38:41], v[18:25], v[232:239], v[38:41]
	v_mfma_f32_16x16x128_f8f6f4 v[34:37], v[26:33], v[232:239], v[34:37]
	s_setprio 0
	s_barrier
	s_add_i32 s82, s82, 2
	s_add_u32 s74, s74, 0x100
	s_addc_u32 s75, s75, 0
	s_add_u32 s80, s80, 0x100
	s_addc_u32 s81, s81, 0
	s_cmp_gt_u32 s82, 29
	s_cbranch_scc0 .LBB0_505
	s_nop 7
	s_nop 7
	s_and_b64 vcc, exec, s[12:13]
	s_cbranch_vccz .LBB0_508
	s_barrier

; #define PG8_STAGE(bufoff, gbase, voff) do { if constexpr (DIAG >= 1) break; _Pragma("unroll") for (int _i = 0; _i < 2; ++_i) \
;         __builtin_amdgcn_global_load_lds((const unsigned*)((const char*)(gbase) + (voff)[_i]), (PG8_LAS unsigned*)(lds + (bufoff) + ldsw + _i * 8192), 16, 0, 0); } while (0)
; #define PG8_LDA(dst, b, h) do { if constexpr (DIAG == 2 || DIAG == 3) break; _Pragma("unroll") for (int m = 0; m < 4; ++m) _Pragma("unroll") for (int k = 0; k < 2; ++k) dst[m][k] = *(const PG8_LAS bf16x8*)(lds + PG8_SA(b, h) + aoff + m * 2048 + k * 1024); } while (0)
; #define PG8_LDB(dst, b, h) do { if constexpr (DIAG == 2 || DIAG == 3) break; _Pragma("unroll") for (int n = 0; n < 2; ++n) _Pragma("unroll") for (int k = 0; k < 2; ++k) dst[n][k] = *(const PG8_LAS bf16x8*)(lds + PG8_SB(b, h) + boff + n * 2048 + k * 1024); } while (0)
; #define PG8_WAIT_V(n) asm volatile("s_waitcnt vmcnt(" #n ")" ::: "memory")
; #define PG8_WAIT_L(n) asm volatile("s_waitcnt lgkmcnt(" #n ")" ::: "memory")
; #define PG8_BAR __builtin_amdgcn_s_barrier()
; #define PG8_LP_ON __builtin_amdgcn_s_setprio(PG8_LOADPRIO)
; #define PG8_LP_OFF __builtin_amdgcn_s_setprio(0)
; #define PG8_LP_ON do {} while (0)
; #define PG8_LP_OFF do {} while (0)
; #define PG8_SCHED __builtin_amdgcn_sched_barrier(0)
;     ...
;             if constexpr (SP2) {
;             PG8_LP_ON; PG8_LDB(B0, 0, 0); PG8_LDB(B1, 0, 1); PG8_SCHED; PG8_LDA(At, 0, 0); PG8_STAGE(PG8_SA(1, 1), a1 + hstep, voffA);
;             PG8_LP_OFF; PG8_WAIT_V(8); PG8_WAIT_L(0); PG8_BAR; PG8_MMA(0, 0, At, B0); PG8_MMA(0, 1, At, B1); PG8_BAR; PG8_SCHED;
;             PG8_LP_ON; PG8_LDA(At, 0, 1); PG8_STAGE(PG8_SB(0, 0), b2, voffB); PG8_STAGE(PG8_SB(0, 1), b2 + hstep, voffB); PG8_STAGE(PG8_SA(0, 0), a2, voffA);
;             PG8_LP_OFF; PG8_WAIT_V(8); PG8_WAIT_L(0); PG8_BAR; PG8_MMA(1, 0, At, B0); PG8_MMA(1, 1, At, B1); PG8_BAR; PG8_SCHED;
.LBB0_521:
	ds_read_b128 v[146:149], v153
	ds_read_b128 v[156:159], v153 offset:1024
	ds_read_b128 v[166:169], v153 offset:2048
	ds_read_b128 v[170:173], v153 offset:3072
	ds_read_b128 v[174:177], v154
	ds_read_b128 v[178:181], v154 offset:1024
	ds_read_b128 v[182:185], v154 offset:2048
	ds_read_b128 v[186:189], v154 offset:3072
	ds_read_b128 v[192:195], v155
	ds_read_b128 v[196:199], v155 offset:1024
	ds_read_b128 v[200:203], v155 offset:2048
	ds_read_b128 v[204:207], v155 offset:3072
	ds_read_b128 v[208:211], v155 offset:4096
	ds_read_b128 v[212:215], v155 offset:5120
	ds_read_b128 v[216:219], v155 offset:6144
	ds_read_b128 v[220:223], v155 offset:7168
	s_add_u32 s74, s72, 0xfff00080
	s_addc_u32 s75, s73, -1
	s_cmp_eq_u32 s91, 60
	s_cselect_b32 s77, s17, s75
	s_cselect_b32 s76, s80, s74
	s_cselect_b32 s75, s15, s83
	s_cselect_b32 s74, s81, s82
	v_lshl_add_u64 v[160:161], s[72:73], 0, v[138:139]
	s_add_i32 m0, s23, 0xc000
	s_nop 0
	global_load_lds_dwordx4 v[160:161], off
	v_lshl_add_u64 v[160:161], s[72:73], 0, v[140:141]
	s_add_i32 m0, s23, 0xe000
	s_nop 0
	global_load_lds_dwordx4 v[160:161], off
	s_waitcnt vmcnt(8)
	s_waitcnt lgkmcnt(0)
	s_barrier
	s_setprio 1
	s_waitcnt lgkmcnt(0)
	v_mfma_f32_16x16x32_bf16 v[126:129], v[146:149], v[192:195], v[126:129]
	v_mfma_f32_16x16x32_bf16 v[122:125], v[166:169], v[192:195], v[122:125]
	v_mfma_f32_16x16x32_bf16 v[118:121], v[146:149], v[200:203], v[118:121]
	v_mfma_f32_16x16x32_bf16 v[110:113], v[166:169], v[200:203], v[110:113]
	v_mfma_f32_16x16x32_bf16 v[102:105], v[146:149], v[208:211], v[102:105]
	v_mfma_f32_16x16x32_bf16 v[94:97], v[166:169], v[208:211], v[94:97]
	v_mfma_f32_16x16x32_bf16 v[86:89], v[146:149], v[216:219], v[86:89]
	v_mfma_f32_16x16x32_bf16 v[78:81], v[166:169], v[216:219], v[78:81]
	v_mfma_f32_16x16x32_bf16 v[126:129], v[156:159], v[196:199], v[126:129]
	v_mfma_f32_16x16x32_bf16 v[122:125], v[170:173], v[196:199], v[122:125]
	v_mfma_f32_16x16x32_bf16 v[118:121], v[156:159], v[204:207], v[118:121]
	v_mfma_f32_16x16x32_bf16 v[110:113], v[170:173], v[204:207], v[110:113]
	v_mfma_f32_16x16x32_bf16 v[102:105], v[156:159], v[212:215], v[102:105]
	v_mfma_f32_16x16x32_bf16 v[94:97], v[170:173], v[212:215], v[94:97]
	v_mfma_f32_16x16x32_bf16 v[86:89], v[156:159], v[220:223], v[86:89]
	v_mfma_f32_16x16x32_bf16 v[78:81], v[170:173], v[220:223], v[78:81]
	s_setprio 0
	s_setprio 1
	v_mfma_f32_16x16x32_bf16 v[114:117], v[174:177], v[192:195], v[114:117]
	v_mfma_f32_16x16x32_bf16 v[106:109], v[182:185], v[192:195], v[106:109]
	v_mfma_f32_16x16x32_bf16 v[98:101], v[174:177], v[200:203], v[98:101]
	v_mfma_f32_16x16x32_bf16 v[90:93], v[182:185], v[200:203], v[90:93]
	v_mfma_f32_16x16x32_bf16 v[82:85], v[174:177], v[208:211], v[82:85]
	v_mfma_f32_16x16x32_bf16 v[74:77], v[182:185], v[208:211], v[74:77]
	v_mfma_f32_16x16x32_bf16 v[70:73], v[174:177], v[216:219], v[70:73]
	v_mfma_f32_16x16x32_bf16 v[66:69], v[182:185], v[216:219], v[66:69]
	v_mfma_f32_16x16x32_bf16 v[114:117], v[178:181], v[196:199], v[114:117]
	v_mfma_f32_16x16x32_bf16 v[106:109], v[186:189], v[196:199], v[106:109]
	v_mfma_f32_16x16x32_bf16 v[98:101], v[178:181], v[204:207], v[98:101]
	v_mfma_f32_16x16x32_bf16 v[90:93], v[186:189], v[204:207], v[90:93]
	v_mfma_f32_16x16x32_bf16 v[82:85], v[178:181], v[212:215], v[82:85]
	v_mfma_f32_16x16x32_bf16 v[74:77], v[186:189], v[212:215], v[74:77]
	v_mfma_f32_16x16x32_bf16 v[70:73], v[178:181], v[220:223], v[70:73]
	v_mfma_f32_16x16x32_bf16 v[66:69], v[186:189], v[220:223], v[66:69]
	s_setprio 0
	s_barrier
	ds_read_b128 v[192:195], v155 offset:16384
	ds_read_b128 v[196:199], v155 offset:17408
	ds_read_b128 v[200:203], v155 offset:18432
	ds_read_b128 v[204:207], v155 offset:19456
	ds_read_b128 v[208:211], v155 offset:20480
	ds_read_b128 v[212:215], v155 offset:21504
	ds_read_b128 v[216:219], v155 offset:22528
	ds_read_b128 v[220:223], v155 offset:23552
	s_add_i32 s92, s88, s27
	v_lshl_add_u64 v[160:161], s[74:75], 0, v[132:133]
	s_mov_b32 m0, s92
	s_nop 0
	global_load_lds_dwordx4 v[160:161], off
	s_add_i32 m0, s92, 0x2000
	s_add_u32 s92, s74, 0x100000
	v_lshl_add_u64 v[224:225], s[74:75], 0, v[136:137]
	s_addc_u32 s93, s75, 0
	s_add_i32 s94, s89, s27
	global_load_lds_dwordx4 v[224:225], off
	v_lshl_add_u64 v[226:227], s[92:93], 0, v[132:133]
	s_mov_b32 m0, s94
	v_lshl_add_u64 v[228:229], s[76:77], 0, v[134:135]
	global_load_lds_dwordx4 v[226:227], off
	v_lshl_add_u64 v[226:227], s[92:93], 0, v[136:137]
	s_add_i32 m0, s94, 0x2000
	s_nop 0
	global_load_lds_dwordx4 v[226:227], off
	s_waitcnt vmcnt(6)
	s_waitcnt lgkmcnt(0)
	s_barrier
; #define PG8_STAGE(bufoff, gbase, voff) do { if constexpr (DIAG >= 1) break; _Pragma("unroll") for (int _i = 0; _i < 2; ++_i) \
;         __builtin_amdgcn_global_load_lds((const unsigned*)((const char*)(gbase) + (voff)[_i]), (PG8_LAS unsigned*)(lds + (bufoff) + ldsw + _i * 8192), 16, 0, 0); } while (0)
; #define PG8_LDA(dst, b, h) do { if constexpr (DIAG == 2 || DIAG == 3) break; _Pragma("unroll") for (int m = 0; m < 4; ++m) _Pragma("unroll") for (int k = 0; k < 2; ++k) dst[m][k] = *(const PG8_LAS bf16x8*)(lds + PG8_SA(b, h) + aoff + m * 2048 + k * 1024); } while (0)
; #define PG8_LDB(dst, b, h) do { if constexpr (DIAG == 2 || DIAG == 3) break; _Pragma("unroll") for (int n = 0; n < 2; ++n) _Pragma("unroll") for (int k = 0; k < 2; ++k) dst[n][k] = *(const PG8_LAS bf16x8*)(lds + PG8_SB(b, h) + boff + n * 2048 + k * 1024); } while (0)
; #define PG8_WAIT_V(n) asm volatile("s_waitcnt vmcnt(" #n ")" ::: "memory")
; #define PG8_WAIT_L(n) asm volatile("s_waitcnt lgkmcnt(" #n ")" ::: "memory")
; #define PG8_BAR __builtin_amdgcn_s_barrier()
; #define PG8_LP_ON __builtin_amdgcn_s_setprio(PG8_LOADPRIO)
; #define PG8_LP_OFF __builtin_amdgcn_s_setprio(0)
; #define PG8_LP_ON do {} while (0)
; #define PG8_LP_OFF do {} while (0)
; #define PG8_SCHED __builtin_amdgcn_sched_barrier(0)
;     ...
;             PG8_LP_OFF; PG8_WAIT_V(8); PG8_WAIT_L(0); PG8_BAR; PG8_MMA(1, 0, At, B0); PG8_MMA(1, 1, At, B1); PG8_BAR; PG8_SCHED;
;             PG8_LP_ON; PG8_LDB(B0, 1, 0); PG8_LDB(B1, 1, 1); PG8_SCHED; PG8_LDA(At, 1, 0); PG8_STAGE(PG8_SA(0, 1), a2 + hstep, voffA);
;             PG8_LP_OFF; PG8_WAIT_V(8); PG8_WAIT_L(0); PG8_BAR; PG8_MMA(0, 0, At, B0); PG8_MMA(0, 1, At, B1); PG8_BAR; PG8_SCHED;
	s_setprio 1
	s_waitcnt lgkmcnt(0)
	v_mfma_f32_16x16x32_bf16 v[62:65], v[146:149], v[192:195], v[62:65]
	v_mfma_f32_16x16x32_bf16 v[58:61], v[166:169], v[192:195], v[58:61]
	v_mfma_f32_16x16x32_bf16 v[54:57], v[146:149], v[200:203], v[54:57]
	v_mfma_f32_16x16x32_bf16 v[46:49], v[166:169], v[200:203], v[46:49]
	v_mfma_f32_16x16x32_bf16 v[38:41], v[146:149], v[208:211], v[38:41]
	v_mfma_f32_16x16x32_bf16 v[30:33], v[166:169], v[208:211], v[30:33]
	v_mfma_f32_16x16x32_bf16 v[22:25], v[146:149], v[216:219], v[22:25]
	v_mfma_f32_16x16x32_bf16 v[14:17], v[166:169], v[216:219], v[14:17]
	v_mfma_f32_16x16x32_bf16 v[62:65], v[156:159], v[196:199], v[62:65]
	v_lshl_add_u64 v[226:227], s[76:77], 0, v[130:131]
	s_mov_b32 m0, s23
	s_nop 0
	global_load_lds_dwordx4 v[226:227], off
	v_mfma_f32_16x16x32_bf16 v[58:61], v[170:173], v[196:199], v[58:61]
	v_mfma_f32_16x16x32_bf16 v[54:57], v[156:159], v[204:207], v[54:57]
	v_mfma_f32_16x16x32_bf16 v[46:49], v[170:173], v[204:207], v[46:49]
	v_mfma_f32_16x16x32_bf16 v[38:41], v[156:159], v[212:215], v[38:41]
	v_mfma_f32_16x16x32_bf16 v[30:33], v[170:173], v[212:215], v[30:33]
	v_mfma_f32_16x16x32_bf16 v[22:25], v[156:159], v[220:223], v[22:25]
	v_mfma_f32_16x16x32_bf16 v[14:17], v[170:173], v[220:223], v[14:17]
	s_setprio 0
	s_setprio 1
	v_mfma_f32_16x16x32_bf16 v[50:53], v[174:177], v[192:195], v[50:53]
	v_mfma_f32_16x16x32_bf16 v[42:45], v[182:185], v[192:195], v[42:45]
	v_mfma_f32_16x16x32_bf16 v[34:37], v[174:177], v[200:203], v[34:37]
	v_mfma_f32_16x16x32_bf16 v[26:29], v[182:185], v[200:203], v[26:29]
	v_mfma_f32_16x16x32_bf16 v[18:21], v[174:177], v[208:211], v[18:21]
	v_mfma_f32_16x16x32_bf16 v[10:13], v[182:185], v[208:211], v[10:13]
	v_mfma_f32_16x16x32_bf16 v[6:9], v[174:177], v[216:219], v[6:9]
	v_mfma_f32_16x16x32_bf16 v[2:5], v[182:185], v[216:219], v[2:5]
	v_mfma_f32_16x16x32_bf16 v[50:53], v[178:181], v[196:199], v[50:53]
	s_mov_b32 m0, s26
	s_nop 0
	global_load_lds_dwordx4 v[228:229], off
	v_mfma_f32_16x16x32_bf16 v[42:45], v[186:189], v[196:199], v[42:45]
	v_mfma_f32_16x16x32_bf16 v[34:37], v[178:181], v[204:207], v[34:37]
	v_mfma_f32_16x16x32_bf16 v[26:29], v[186:189], v[204:207], v[26:29]
	v_mfma_f32_16x16x32_bf16 v[18:21], v[178:181], v[212:215], v[18:21]
	v_mfma_f32_16x16x32_bf16 v[10:13], v[186:189], v[212:215], v[10:13]
	v_mfma_f32_16x16x32_bf16 v[6:9], v[178:181], v[220:223], v[6:9]
	v_mfma_f32_16x16x32_bf16 v[2:5], v[186:189], v[220:223], v[2:5]
	s_setprio 0
	s_barrier
	s_add_i32 s92, 0, 0x18000
	v_add_u32_e32 v165, s92, v151
	s_add_i32 s93, 0, 0x1c000
	ds_read_b128 v[146:149], v165
	ds_read_b128 v[156:159], v165 offset:1024
	ds_read_b128 v[166:169], v165 offset:2048
	ds_read_b128 v[170:173], v165 offset:3072
	v_add_u32_e32 v165, s93, v151
	ds_read_b128 v[174:177], v165
	ds_read_b128 v[178:181], v165 offset:1024
	ds_read_b128 v[182:185], v165 offset:2048
	ds_read_b128 v[186:189], v165 offset:3072
	ds_read_b128 v[192:195], v155 offset:32768
	ds_read_b128 v[196:199], v155 offset:33792
	ds_read_b128 v[200:203], v155 offset:34816
	ds_read_b128 v[204:207], v155 offset:35840
	ds_read_b128 v[208:211], v155 offset:36864
	ds_read_b128 v[212:215], v155 offset:37888
	ds_read_b128 v[216:219], v155 offset:38912
	ds_read_b128 v[220:223], v155 offset:39936
	s_add_u32 s76, s76, 0x100000
	s_addc_u32 s77, s77, 0
	s_mov_b32 m0, s55
	v_lshl_add_u64 v[230:231], s[76:77], 0, v[130:131]
	global_load_lds_dwordx4 v[230:231], off
	v_lshl_add_u64 v[230:231], s[76:77], 0, v[134:135]
	s_mov_b32 m0, s84
	s_nop 0
	global_load_lds_dwordx4 v[230:231], off
	s_waitcnt vmcnt(8)
	s_waitcnt lgkmcnt(0)
	s_barrier
	s_setprio 1
	s_waitcnt lgkmcnt(0)
	v_mfma_f32_16x16x32_bf16 v[126:129], v[146:149], v[192:195], v[126:129]
	v_mfma_f32_16x16x32_bf16 v[122:125], v[166:169], v[192:195], v[122:125]
	v_mfma_f32_16x16x32_bf16 v[118:121], v[146:149], v[200:203], v[118:121]
	v_mfma_f32_16x16x32_bf16 v[110:113], v[166:169], v[200:203], v[110:113]
	v_mfma_f32_16x16x32_bf16 v[102:105], v[146:149], v[208:211], v[102:105]
	v_mfma_f32_16x16x32_bf16 v[94:97], v[166:169], v[208:211], v[94:97]
	v_mfma_f32_16x16x32_bf16 v[86:89], v[146:149], v[216:219], v[86:89]
	v_mfma_f32_16x16x32_bf16 v[78:81], v[166:169], v[216:219], v[78:81]
	v_mfma_f32_16x16x32_bf16 v[126:129], v[156:159], v[196:199], v[126:129]
	v_mfma_f32_16x16x32_bf16 v[122:125], v[170:173], v[196:199], v[122:125]
	v_mfma_f32_16x16x32_bf16 v[118:121], v[156:159], v[204:207], v[118:121]
	v_mfma_f32_16x16x32_bf16 v[110:113], v[170:173], v[204:207], v[110:113]
	v_mfma_f32_16x16x32_bf16 v[102:105], v[156:159], v[212:215], v[102:105]
	v_mfma_f32_16x16x32_bf16 v[94:97], v[170:173], v[212:215], v[94:97]
	v_mfma_f32_16x16x32_bf16 v[86:89], v[156:159], v[220:223], v[86:89]
	v_mfma_f32_16x16x32_bf16 v[78:81], v[170:173], v[220:223], v[78:81]
	s_setprio 0
	s_setprio 1
	v_mfma_f32_16x16x32_bf16 v[114:117], v[174:177], v[192:195], v[114:117]
	v_mfma_f32_16x16x32_bf16 v[106:109], v[182:185], v[192:195], v[106:109]
	v_mfma_f32_16x16x32_bf16 v[98:101], v[174:177], v[200:203], v[98:101]
	v_mfma_f32_16x16x32_bf16 v[90:93], v[182:185], v[200:203], v[90:93]
	v_mfma_f32_16x16x32_bf16 v[82:85], v[174:177], v[208:211], v[82:85]
	v_mfma_f32_16x16x32_bf16 v[74:77], v[182:185], v[208:211], v[74:77]
	v_mfma_f32_16x16x32_bf16 v[70:73], v[174:177], v[216:219], v[70:73]
	v_mfma_f32_16x16x32_bf16 v[66:69], v[182:185], v[216:219], v[66:69]
	v_mfma_f32_16x16x32_bf16 v[114:117], v[178:181], v[196:199], v[114:117]
	v_mfma_f32_16x16x32_bf16 v[106:109], v[186:189], v[196:199], v[106:109]
	v_mfma_f32_16x16x32_bf16 v[98:101], v[178:181], v[204:207], v[98:101]
	v_mfma_f32_16x16x32_bf16 v[90:93], v[186:189], v[204:207], v[90:93]
	v_mfma_f32_16x16x32_bf16 v[82:85], v[178:181], v[212:215], v[82:85]
	v_mfma_f32_16x16x32_bf16 v[74:77], v[186:189], v[212:215], v[74:77]
	v_mfma_f32_16x16x32_bf16 v[70:73], v[178:181], v[220:223], v[70:73]
	v_mfma_f32_16x16x32_bf16 v[66:69], v[186:189], v[220:223], v[66:69]
	s_setprio 0
	s_barrier
; #define PG8_STAGE(bufoff, gbase, voff) do { if constexpr (DIAG >= 1) break; _Pragma("unroll") for (int _i = 0; _i < 2; ++_i) \
;         __builtin_amdgcn_global_load_lds((const unsigned*)((const char*)(gbase) + (voff)[_i]), (PG8_LAS unsigned*)(lds + (bufoff) + ldsw + _i * 8192), 16, 0, 0); } while (0)
; #define PG8_LDA(dst, b, h) do { if constexpr (DIAG == 2 || DIAG == 3) break; _Pragma("unroll") for (int m = 0; m < 4; ++m) _Pragma("unroll") for (int k = 0; k < 2; ++k) dst[m][k] = *(const PG8_LAS bf16x8*)(lds + PG8_SA(b, h) + aoff + m * 2048 + k * 1024); } while (0)
; #define PG8_WAIT_V(n) asm volatile("s_waitcnt vmcnt(" #n ")" ::: "memory")
; #define PG8_WAIT_L(n) asm volatile("s_waitcnt lgkmcnt(" #n ")" ::: "memory")
; #define PG8_BAR __builtin_amdgcn_s_barrier()
; #define PG8_LP_OFF __builtin_amdgcn_s_setprio(0)
;     ...
;         for (int t = kb; t < ke; t += 2) {
;             const bool last = (t == ke - 2);
;             const char* a1 = cA + (size_t)(t + 1) * kstep;
;             const char* a2 = last ? nA : cA + (size_t)(t + 2) * kstep; const char* b2 = last ? nB : cB + (size_t)(t + 2) * kstep;
;             const char* a3 = a2 + kstep; const char* b3 = b2 + kstep;
;             if (last && has_next) S.a_ready(nxt);
;             if constexpr (SP2) {
;             PG8_LP_ON; PG8_LDB(B0, 0, 0); PG8_LDB(B1, 0, 1); PG8_SCHED; PG8_LDA(At, 0, 0); PG8_STAGE(PG8_SA(1, 1), a1 + hstep, voffA);
;             PG8_LP_OFF; PG8_WAIT_V(8); PG8_WAIT_L(0); PG8_BAR; PG8_MMA(0, 0, At, B0); PG8_MMA(0, 1, At, B1); PG8_BAR; PG8_SCHED;
;             PG8_LP_ON; PG8_LDA(At, 0, 1); PG8_STAGE(PG8_SB(0, 0), b2, voffB); PG8_STAGE(PG8_SB(0, 1), b2 + hstep, voffB); PG8_STAGE(PG8_SA(0, 0), a2, voffA);
;             PG8_LP_OFF; PG8_WAIT_V(8); PG8_WAIT_L(0); PG8_BAR; PG8_MMA(1, 0, At, B0); PG8_MMA(1, 1, At, B1); PG8_BAR; PG8_SCHED;
;             PG8_LP_ON; PG8_LDB(B0, 1, 0); PG8_LDB(B1, 1, 1); PG8_SCHED; PG8_LDA(At, 1, 0); PG8_STAGE(PG8_SA(0, 1), a2 + hstep, voffA);
;             PG8_LP_OFF; PG8_WAIT_V(8); PG8_WAIT_L(0); PG8_BAR; PG8_MMA(0, 0, At, B0); PG8_MMA(0, 1, At, B1); PG8_BAR; PG8_SCHED;
;             PG8_LP_ON; PG8_LDA(At, 1, 1); PG8_STAGE(PG8_SB(1, 0), b3, voffB); PG8_STAGE(PG8_SB(1, 1), b3 + hstep, voffB); PG8_STAGE(PG8_SA(1, 0), a3, voffA);
;             PG8_LP_OFF; PG8_WAIT_V(8); PG8_WAIT_L(0); PG8_BAR; PG8_MMA(1, 0, At, B0); PG8_MMA(1, 1, At, B1); PG8_BAR; PG8_SCHED;
	ds_read_b128 v[192:195], v155 offset:49152
	ds_read_b128 v[196:199], v155 offset:50176
	ds_read_b128 v[200:203], v155 offset:51200
	ds_read_b128 v[204:207], v155 offset:52224
	ds_read_b128 v[208:211], v155 offset:53248
	ds_read_b128 v[212:215], v155 offset:54272
	ds_read_b128 v[216:219], v155 offset:55296
	ds_read_b128 v[220:223], v155 offset:56320
	s_add_i32 s76, s92, s27
	v_lshl_add_u64 v[160:161], v[160:161], 0, s[10:11]
	s_mov_b32 m0, s76
	s_nop 0
	global_load_lds_dwordx4 v[160:161], off
	s_add_i32 m0, s76, 0x2000
	s_add_u32 s74, s74, 0x100080
	v_lshl_add_u64 v[160:161], v[224:225], 0, s[10:11]
	s_addc_u32 s75, s75, 0
	s_add_i32 s76, s93, s27
	global_load_lds_dwordx4 v[160:161], off
	v_lshl_add_u64 v[160:161], s[74:75], 0, v[132:133]
	s_mov_b32 m0, s76
	s_nop 0
	global_load_lds_dwordx4 v[160:161], off
	v_lshl_add_u64 v[160:161], s[74:75], 0, v[136:137]
	s_add_i32 m0, s76, 0x2000
	s_nop 0
	global_load_lds_dwordx4 v[160:161], off
	s_waitcnt vmcnt(6)
	s_waitcnt lgkmcnt(0)
	s_barrier
	s_setprio 1
	s_waitcnt lgkmcnt(0)
	v_mfma_f32_16x16x32_bf16 v[62:65], v[146:149], v[192:195], v[62:65]
	v_mfma_f32_16x16x32_bf16 v[58:61], v[166:169], v[192:195], v[58:61]
	v_mfma_f32_16x16x32_bf16 v[54:57], v[146:149], v[200:203], v[54:57]
	v_mfma_f32_16x16x32_bf16 v[46:49], v[166:169], v[200:203], v[46:49]
	v_mfma_f32_16x16x32_bf16 v[38:41], v[146:149], v[208:211], v[38:41]
	v_mfma_f32_16x16x32_bf16 v[30:33], v[166:169], v[208:211], v[30:33]
	v_mfma_f32_16x16x32_bf16 v[22:25], v[146:149], v[216:219], v[22:25]
	v_mfma_f32_16x16x32_bf16 v[14:17], v[166:169], v[216:219], v[14:17]
	v_mfma_f32_16x16x32_bf16 v[62:65], v[156:159], v[196:199], v[62:65]
	v_lshl_add_u64 v[160:161], v[226:227], 0, s[10:11]
	s_mov_b32 m0, s86
	s_nop 0
	global_load_lds_dwordx4 v[160:161], off
	v_mfma_f32_16x16x32_bf16 v[58:61], v[170:173], v[196:199], v[58:61]
	v_mfma_f32_16x16x32_bf16 v[54:57], v[156:159], v[204:207], v[54:57]
	v_mfma_f32_16x16x32_bf16 v[46:49], v[170:173], v[204:207], v[46:49]
	v_mfma_f32_16x16x32_bf16 v[38:41], v[156:159], v[212:215], v[38:41]
	v_mfma_f32_16x16x32_bf16 v[30:33], v[170:173], v[212:215], v[30:33]
	v_mfma_f32_16x16x32_bf16 v[22:25], v[156:159], v[220:223], v[22:25]
	v_mfma_f32_16x16x32_bf16 v[14:17], v[170:173], v[220:223], v[14:17]
	s_setprio 0
	s_setprio 1
	v_mfma_f32_16x16x32_bf16 v[50:53], v[174:177], v[192:195], v[50:53]
	v_mfma_f32_16x16x32_bf16 v[42:45], v[182:185], v[192:195], v[42:45]
	v_mfma_f32_16x16x32_bf16 v[34:37], v[174:177], v[200:203], v[34:37]
	v_mfma_f32_16x16x32_bf16 v[26:29], v[182:185], v[200:203], v[26:29]
	v_mfma_f32_16x16x32_bf16 v[18:21], v[174:177], v[208:211], v[18:21]
	v_mfma_f32_16x16x32_bf16 v[10:13], v[182:185], v[208:211], v[10:13]
	v_mfma_f32_16x16x32_bf16 v[6:9], v[174:177], v[216:219], v[6:9]
	v_mfma_f32_16x16x32_bf16 v[2:5], v[182:185], v[216:219], v[2:5]
	v_mfma_f32_16x16x32_bf16 v[50:53], v[178:181], v[196:199], v[50:53]
	v_lshl_add_u64 v[160:161], v[228:229], 0, s[10:11]
	s_mov_b32 m0, s87
	s_nop 0
	global_load_lds_dwordx4 v[160:161], off
	v_mfma_f32_16x16x32_bf16 v[42:45], v[186:189], v[196:199], v[42:45]
	v_mfma_f32_16x16x32_bf16 v[34:37], v[178:181], v[204:207], v[34:37]
	v_mfma_f32_16x16x32_bf16 v[26:29], v[186:189], v[204:207], v[26:29]
	v_mfma_f32_16x16x32_bf16 v[18:21], v[178:181], v[212:215], v[18:21]
	v_mfma_f32_16x16x32_bf16 v[10:13], v[186:189], v[212:215], v[10:13]
	v_mfma_f32_16x16x32_bf16 v[6:9], v[178:181], v[220:223], v[6:9]
	v_mfma_f32_16x16x32_bf16 v[2:5], v[186:189], v[220:223], v[2:5]
	s_setprio 0
	s_barrier
	s_add_i32 s91, s91, 2
	s_add_u32 s72, s72, 0x100
	s_addc_u32 s73, s73, 0
	s_add_u32 s82, s82, 0x100
	s_addc_u32 s83, s83, 0
	s_cmp_gt_u32 s91, 61
	s_cbranch_scc0 .LBB0_521
	s_and_b64 vcc, exec, s[12:13]
	s_cbranch_vccz .LBB0_524
	s_barrier

; #define PG8_STAGE(bufoff, gbase, voff) do { if constexpr (DIAG >= 1) break; _Pragma("unroll") for (int _i = 0; _i < 2; ++_i) \
;         __builtin_amdgcn_global_load_lds((const unsigned*)((const char*)(gbase) + (voff)[_i]), (PG8_LAS unsigned*)(lds + (bufoff) + ldsw + _i * 8192), 16, 0, 0); } while (0)
; #define PG8_LDA(dst, b, h) do { if constexpr (DIAG == 2 || DIAG == 3) break; _Pragma("unroll") for (int m = 0; m < 4; ++m) _Pragma("unroll") for (int k = 0; k < 2; ++k) dst[m][k] = *(const PG8_LAS bf16x8*)(lds + PG8_SA(b, h) + aoff + m * 2048 + k * 1024); } while (0)
; #define PG8_LDB(dst, b, h) do { if constexpr (DIAG == 2 || DIAG == 3) break; _Pragma("unroll") for (int n = 0; n < 2; ++n) _Pragma("unroll") for (int k = 0; k < 2; ++k) dst[n][k] = *(const PG8_LAS bf16x8*)(lds + PG8_SB(b, h) + boff + n * 2048 + k * 1024); } while (0)
; #define PG8_WAIT_V(n) asm volatile("s_waitcnt vmcnt(" #n ")" ::: "memory")
; #define PG8_WAIT_L(n) asm volatile("s_waitcnt lgkmcnt(" #n ")" ::: "memory")
; #define PG8_BAR __builtin_amdgcn_s_barrier()
; #define PG8_LP_ON __builtin_amdgcn_s_setprio(PG8_LOADPRIO)
; #define PG8_LP_OFF __builtin_amdgcn_s_setprio(0)
; #define PG8_LP_ON do {} while (0)
; #define PG8_LP_OFF do {} while (0)
; #define PG8_SCHED __builtin_amdgcn_sched_barrier(0)
;     ...
;         for (int t = kb; t < ke; t += 2) {
;             const bool last = (t == ke - 2);
;             const char* a1 = cA + (size_t)(t + 1) * kstep;
;             const char* a2 = last ? nA : cA + (size_t)(t + 2) * kstep; const char* b2 = last ? nB : cB + (size_t)(t + 2) * kstep;
;             const char* a3 = a2 + kstep; const char* b3 = b2 + kstep;
;             if (last && has_next) S.a_ready(nxt);
;             if constexpr (SP2) {
;             PG8_LP_ON; PG8_LDB(B0, 0, 0); PG8_LDB(B1, 0, 1); PG8_SCHED; PG8_LDA(At, 0, 0); PG8_STAGE(PG8_SA(1, 1), a1 + hstep, voffA);
;             PG8_LP_OFF; PG8_WAIT_V(8); PG8_WAIT_L(0); PG8_BAR; PG8_MMA(0, 0, At, B0); PG8_MMA(0, 1, At, B1); PG8_BAR; PG8_SCHED;
;             PG8_LP_ON; PG8_LDA(At, 0, 1); PG8_STAGE(PG8_SB(0, 0), b2, voffB); PG8_STAGE(PG8_SB(0, 1), b2 + hstep, voffB); PG8_STAGE(PG8_SA(0, 0), a2, voffA);
;             PG8_LP_OFF; PG8_WAIT_V(8); PG8_WAIT_L(0); PG8_BAR; PG8_MMA(1, 0, At, B0); PG8_MMA(1, 1, At, B1); PG8_BAR; PG8_SCHED;
.LBB0_725:
	ds_read_b128 v[130:133], v177
	ds_read_b128 v[134:137], v177 offset:1024
	ds_read_b128 v[138:141], v177 offset:2048
	ds_read_b128 v[142:145], v177 offset:3072
	ds_read_b128 v[166:169], v178
	ds_read_b128 v[170:173], v178 offset:1024
	ds_read_b128 v[180:183], v178 offset:2048
	ds_read_b128 v[184:187], v178 offset:3072
	ds_read_b128 v[188:191], v179
	ds_read_b128 v[192:195], v179 offset:1024
	ds_read_b128 v[196:199], v179 offset:2048
	ds_read_b128 v[200:203], v179 offset:3072
	ds_read_b128 v[204:207], v179 offset:4096
	ds_read_b128 v[208:211], v179 offset:5120
	ds_read_b128 v[212:215], v179 offset:6144
	ds_read_b128 v[216:219], v179 offset:7168
	s_add_u32 s62, s60, 0xfff00080
	s_addc_u32 s63, s61, -1
	s_cmp_eq_u32 s83, 60
	s_cselect_b32 s65, s5, s63
	s_cselect_b32 s64, s26, s62
	s_cselect_b32 s63, s23, s82
	s_cselect_b32 s62, s27, s47
	v_lshl_add_u64 v[160:161], s[60:61], 0, v[152:153]
	s_add_i32 m0, s1, 0xc000
	s_nop 0
	global_load_lds_dwordx4 v[160:161], off
	v_lshl_add_u64 v[160:161], s[60:61], 0, v[154:155]
	s_add_i32 m0, s1, 0xe000
	s_nop 0
	global_load_lds_dwordx4 v[160:161], off
	s_waitcnt vmcnt(8)
	s_waitcnt lgkmcnt(0)
	s_barrier
	s_setprio 1
	s_waitcnt lgkmcnt(0)
	v_mfma_f32_16x16x32_bf16 v[126:129], v[130:133], v[188:191], v[126:129]
	v_mfma_f32_16x16x32_bf16 v[122:125], v[138:141], v[188:191], v[122:125]
	v_mfma_f32_16x16x32_bf16 v[110:113], v[130:133], v[196:199], v[110:113]
	v_mfma_f32_16x16x32_bf16 v[106:109], v[138:141], v[196:199], v[106:109]
	v_mfma_f32_16x16x32_bf16 v[94:97], v[130:133], v[204:207], v[94:97]
	v_mfma_f32_16x16x32_bf16 v[90:93], v[138:141], v[204:207], v[90:93]
	v_mfma_f32_16x16x32_bf16 v[78:81], v[130:133], v[212:215], v[78:81]
	v_mfma_f32_16x16x32_bf16 v[74:77], v[138:141], v[212:215], v[74:77]
	v_mfma_f32_16x16x32_bf16 v[126:129], v[134:137], v[192:195], v[126:129]
	v_mfma_f32_16x16x32_bf16 v[122:125], v[142:145], v[192:195], v[122:125]
	v_mfma_f32_16x16x32_bf16 v[110:113], v[134:137], v[200:203], v[110:113]
	v_mfma_f32_16x16x32_bf16 v[106:109], v[142:145], v[200:203], v[106:109]
	v_mfma_f32_16x16x32_bf16 v[94:97], v[134:137], v[208:211], v[94:97]
	v_mfma_f32_16x16x32_bf16 v[90:93], v[142:145], v[208:211], v[90:93]
	v_mfma_f32_16x16x32_bf16 v[78:81], v[134:137], v[216:219], v[78:81]
	v_mfma_f32_16x16x32_bf16 v[74:77], v[142:145], v[216:219], v[74:77]
	s_setprio 0
	s_setprio 1
	v_mfma_f32_16x16x32_bf16 v[118:121], v[166:169], v[188:191], v[118:121]
	v_mfma_f32_16x16x32_bf16 v[114:117], v[180:183], v[188:191], v[114:117]
	v_mfma_f32_16x16x32_bf16 v[102:105], v[166:169], v[196:199], v[102:105]
	v_mfma_f32_16x16x32_bf16 v[98:101], v[180:183], v[196:199], v[98:101]
	v_mfma_f32_16x16x32_bf16 v[86:89], v[166:169], v[204:207], v[86:89]
	v_mfma_f32_16x16x32_bf16 v[82:85], v[180:183], v[204:207], v[82:85]
	v_mfma_f32_16x16x32_bf16 v[70:73], v[166:169], v[212:215], v[70:73]
	v_mfma_f32_16x16x32_bf16 v[66:69], v[180:183], v[212:215], v[66:69]
	v_mfma_f32_16x16x32_bf16 v[118:121], v[170:173], v[192:195], v[118:121]
	v_mfma_f32_16x16x32_bf16 v[114:117], v[184:187], v[192:195], v[114:117]
	v_mfma_f32_16x16x32_bf16 v[102:105], v[170:173], v[200:203], v[102:105]
	v_mfma_f32_16x16x32_bf16 v[98:101], v[184:187], v[200:203], v[98:101]
	v_mfma_f32_16x16x32_bf16 v[86:89], v[170:173], v[208:211], v[86:89]
	v_mfma_f32_16x16x32_bf16 v[82:85], v[184:187], v[208:211], v[82:85]
	v_mfma_f32_16x16x32_bf16 v[70:73], v[170:173], v[216:219], v[70:73]
	v_mfma_f32_16x16x32_bf16 v[66:69], v[184:187], v[216:219], v[66:69]
	s_setprio 0
	s_barrier
	ds_read_b128 v[188:191], v179 offset:16384
	ds_read_b128 v[192:195], v179 offset:17408
	ds_read_b128 v[196:199], v179 offset:18432
	ds_read_b128 v[200:203], v179 offset:19456
	ds_read_b128 v[204:207], v179 offset:20480
	ds_read_b128 v[208:211], v179 offset:21504
	ds_read_b128 v[212:215], v179 offset:22528
	ds_read_b128 v[216:219], v179 offset:23552
	s_add_i32 s84, s78, s0
	v_lshl_add_u64 v[160:161], s[62:63], 0, v[146:147]
	s_mov_b32 m0, s84
	s_nop 0
	global_load_lds_dwordx4 v[160:161], off
	s_add_i32 m0, s84, 0x2000
	s_add_u32 s84, s62, 0x100000
	v_lshl_add_u64 v[174:175], s[62:63], 0, v[148:149]
	s_addc_u32 s85, s63, 0
	s_add_i32 s86, s79, s0
	global_load_lds_dwordx4 v[174:175], off
	v_lshl_add_u64 v[220:221], s[84:85], 0, v[146:147]
	s_mov_b32 m0, s86
	v_lshl_add_u64 v[222:223], s[64:65], 0, v[148:149]
	global_load_lds_dwordx4 v[220:221], off
	v_lshl_add_u64 v[220:221], s[84:85], 0, v[148:149]
	s_add_i32 m0, s86, 0x2000
	s_nop 0
	global_load_lds_dwordx4 v[220:221], off
	s_waitcnt vmcnt(6)
	s_waitcnt lgkmcnt(0)
	s_barrier
; #define PG8_STAGE(bufoff, gbase, voff) do { if constexpr (DIAG >= 1) break; _Pragma("unroll") for (int _i = 0; _i < 2; ++_i) \
;         __builtin_amdgcn_global_load_lds((const unsigned*)((const char*)(gbase) + (voff)[_i]), (PG8_LAS unsigned*)(lds + (bufoff) + ldsw + _i * 8192), 16, 0, 0); } while (0)
; #define PG8_LDA(dst, b, h) do { if constexpr (DIAG == 2 || DIAG == 3) break; _Pragma("unroll") for (int m = 0; m < 4; ++m) _Pragma("unroll") for (int k = 0; k < 2; ++k) dst[m][k] = *(const PG8_LAS bf16x8*)(lds + PG8_SA(b, h) + aoff + m * 2048 + k * 1024); } while (0)
; #define PG8_LDB(dst, b, h) do { if constexpr (DIAG == 2 || DIAG == 3) break; _Pragma("unroll") for (int n = 0; n < 2; ++n) _Pragma("unroll") for (int k = 0; k < 2; ++k) dst[n][k] = *(const PG8_LAS bf16x8*)(lds + PG8_SB(b, h) + boff + n * 2048 + k * 1024); } while (0)
; #define PG8_WAIT_V(n) asm volatile("s_waitcnt vmcnt(" #n ")" ::: "memory")
; #define PG8_WAIT_L(n) asm volatile("s_waitcnt lgkmcnt(" #n ")" ::: "memory")
; #define PG8_BAR __builtin_amdgcn_s_barrier()
; #define PG8_LP_ON __builtin_amdgcn_s_setprio(PG8_LOADPRIO)
; #define PG8_LP_OFF __builtin_amdgcn_s_setprio(0)
; #define PG8_LP_ON do {} while (0)
; #define PG8_LP_OFF do {} while (0)
; #define PG8_SCHED __builtin_amdgcn_sched_barrier(0)
;     ...
;             PG8_LP_OFF; PG8_WAIT_V(8); PG8_WAIT_L(0); PG8_BAR; PG8_MMA(1, 0, At, B0); PG8_MMA(1, 1, At, B1); PG8_BAR; PG8_SCHED;
;             PG8_LP_ON; PG8_LDB(B0, 1, 0); PG8_LDB(B1, 1, 1); PG8_SCHED; PG8_LDA(At, 1, 0); PG8_STAGE(PG8_SA(0, 1), a2 + hstep, voffA);
;             PG8_LP_OFF; PG8_WAIT_V(8); PG8_WAIT_L(0); PG8_BAR; PG8_MMA(0, 0, At, B0); PG8_MMA(0, 1, At, B1); PG8_BAR; PG8_SCHED;
	s_setprio 1
	s_waitcnt lgkmcnt(0)
	v_mfma_f32_16x16x32_bf16 v[62:65], v[130:133], v[188:191], v[62:65]
	v_mfma_f32_16x16x32_bf16 v[58:61], v[138:141], v[188:191], v[58:61]
	v_mfma_f32_16x16x32_bf16 v[46:49], v[130:133], v[196:199], v[46:49]
	v_mfma_f32_16x16x32_bf16 v[42:45], v[138:141], v[196:199], v[42:45]
	v_mfma_f32_16x16x32_bf16 v[30:33], v[130:133], v[204:207], v[30:33]
	v_mfma_f32_16x16x32_bf16 v[26:29], v[138:141], v[204:207], v[26:29]
	v_mfma_f32_16x16x32_bf16 v[14:17], v[130:133], v[212:215], v[14:17]
	v_mfma_f32_16x16x32_bf16 v[10:13], v[138:141], v[212:215], v[10:13]
	v_mfma_f32_16x16x32_bf16 v[62:65], v[134:137], v[192:195], v[62:65]
	v_lshl_add_u64 v[220:221], s[64:65], 0, v[146:147]
	s_mov_b32 m0, s1
	s_nop 0
	global_load_lds_dwordx4 v[220:221], off
	v_mfma_f32_16x16x32_bf16 v[58:61], v[142:145], v[192:195], v[58:61]
	v_mfma_f32_16x16x32_bf16 v[46:49], v[134:137], v[200:203], v[46:49]
	v_mfma_f32_16x16x32_bf16 v[42:45], v[142:145], v[200:203], v[42:45]
	v_mfma_f32_16x16x32_bf16 v[30:33], v[134:137], v[208:211], v[30:33]
	v_mfma_f32_16x16x32_bf16 v[26:29], v[142:145], v[208:211], v[26:29]
	v_mfma_f32_16x16x32_bf16 v[14:17], v[134:137], v[216:219], v[14:17]
	v_mfma_f32_16x16x32_bf16 v[10:13], v[142:145], v[216:219], v[10:13]
	s_setprio 0
	s_setprio 1
	v_mfma_f32_16x16x32_bf16 v[54:57], v[166:169], v[188:191], v[54:57]
	v_mfma_f32_16x16x32_bf16 v[50:53], v[180:183], v[188:191], v[50:53]
	v_mfma_f32_16x16x32_bf16 v[38:41], v[166:169], v[196:199], v[38:41]
	v_mfma_f32_16x16x32_bf16 v[34:37], v[180:183], v[196:199], v[34:37]
	v_mfma_f32_16x16x32_bf16 v[22:25], v[166:169], v[204:207], v[22:25]
	v_mfma_f32_16x16x32_bf16 v[18:21], v[180:183], v[204:207], v[18:21]
	v_mfma_f32_16x16x32_bf16 v[6:9], v[166:169], v[212:215], v[6:9]
	v_mfma_f32_16x16x32_bf16 v[2:5], v[180:183], v[212:215], v[2:5]
	v_mfma_f32_16x16x32_bf16 v[54:57], v[170:173], v[192:195], v[54:57]
	s_mov_b32 m0, s34
	s_nop 0
	global_load_lds_dwordx4 v[222:223], off
	v_mfma_f32_16x16x32_bf16 v[50:53], v[184:187], v[192:195], v[50:53]
	v_mfma_f32_16x16x32_bf16 v[38:41], v[170:173], v[200:203], v[38:41]
	v_mfma_f32_16x16x32_bf16 v[34:37], v[184:187], v[200:203], v[34:37]
	v_mfma_f32_16x16x32_bf16 v[22:25], v[170:173], v[208:211], v[22:25]
	v_mfma_f32_16x16x32_bf16 v[18:21], v[184:187], v[208:211], v[18:21]
	v_mfma_f32_16x16x32_bf16 v[6:9], v[170:173], v[216:219], v[6:9]
	v_mfma_f32_16x16x32_bf16 v[2:5], v[184:187], v[216:219], v[2:5]
	s_setprio 0
	s_barrier
	s_add_i32 s84, 0, 0x18000
	s_add_i32 s85, 0, 0x1c000
	v_add_u32_e32 v142, s84, v165
	v_add_u32_e32 v150, s85, v165
	ds_read_b128 v[130:133], v142
	ds_read_b128 v[134:137], v142 offset:1024
	ds_read_b128 v[138:141], v142 offset:2048
	ds_read_b128 v[142:145], v142 offset:3072
	ds_read_b128 v[166:169], v150
	ds_read_b128 v[170:173], v150 offset:1024
	ds_read_b128 v[180:183], v150 offset:2048
	ds_read_b128 v[184:187], v150 offset:3072
	ds_read_b128 v[188:191], v179 offset:32768
	ds_read_b128 v[192:195], v179 offset:33792
	ds_read_b128 v[196:199], v179 offset:34816
	ds_read_b128 v[200:203], v179 offset:35840
	ds_read_b128 v[204:207], v179 offset:36864
	ds_read_b128 v[208:211], v179 offset:37888
	ds_read_b128 v[212:215], v179 offset:38912
	ds_read_b128 v[216:219], v179 offset:39936
	s_add_u32 s64, s64, 0x100000
	s_addc_u32 s65, s65, 0
	s_mov_b32 m0, s55
	v_lshl_add_u64 v[224:225], s[64:65], 0, v[146:147]
	global_load_lds_dwordx4 v[224:225], off
	v_lshl_add_u64 v[224:225], s[64:65], 0, v[148:149]
	s_mov_b32 m0, s66
	s_nop 0
	global_load_lds_dwordx4 v[224:225], off
	s_waitcnt vmcnt(8)
	s_waitcnt lgkmcnt(0)
	s_barrier
	s_setprio 1
	s_waitcnt lgkmcnt(0)
	v_mfma_f32_16x16x32_bf16 v[126:129], v[130:133], v[188:191], v[126:129]
	v_mfma_f32_16x16x32_bf16 v[122:125], v[138:141], v[188:191], v[122:125]
	v_mfma_f32_16x16x32_bf16 v[110:113], v[130:133], v[196:199], v[110:113]
	v_mfma_f32_16x16x32_bf16 v[106:109], v[138:141], v[196:199], v[106:109]
	v_mfma_f32_16x16x32_bf16 v[94:97], v[130:133], v[204:207], v[94:97]
	v_mfma_f32_16x16x32_bf16 v[90:93], v[138:141], v[204:207], v[90:93]
	v_mfma_f32_16x16x32_bf16 v[78:81], v[130:133], v[212:215], v[78:81]
	v_mfma_f32_16x16x32_bf16 v[74:77], v[138:141], v[212:215], v[74:77]
	v_mfma_f32_16x16x32_bf16 v[126:129], v[134:137], v[192:195], v[126:129]
	v_mfma_f32_16x16x32_bf16 v[122:125], v[142:145], v[192:195], v[122:125]
	v_mfma_f32_16x16x32_bf16 v[110:113], v[134:137], v[200:203], v[110:113]
	v_mfma_f32_16x16x32_bf16 v[106:109], v[142:145], v[200:203], v[106:109]
	v_mfma_f32_16x16x32_bf16 v[94:97], v[134:137], v[208:211], v[94:97]
	v_mfma_f32_16x16x32_bf16 v[90:93], v[142:145], v[208:211], v[90:93]
	v_mfma_f32_16x16x32_bf16 v[78:81], v[134:137], v[216:219], v[78:81]
	v_mfma_f32_16x16x32_bf16 v[74:77], v[142:145], v[216:219], v[74:77]
	s_setprio 0
	s_setprio 1
	v_mfma_f32_16x16x32_bf16 v[118:121], v[166:169], v[188:191], v[118:121]
	v_mfma_f32_16x16x32_bf16 v[114:117], v[180:183], v[188:191], v[114:117]
	v_mfma_f32_16x16x32_bf16 v[102:105], v[166:169], v[196:199], v[102:105]
	v_mfma_f32_16x16x32_bf16 v[98:101], v[180:183], v[196:199], v[98:101]
	v_mfma_f32_16x16x32_bf16 v[86:89], v[166:169], v[204:207], v[86:89]
	v_mfma_f32_16x16x32_bf16 v[82:85], v[180:183], v[204:207], v[82:85]
	v_mfma_f32_16x16x32_bf16 v[70:73], v[166:169], v[212:215], v[70:73]
	v_mfma_f32_16x16x32_bf16 v[66:69], v[180:183], v[212:215], v[66:69]
	v_mfma_f32_16x16x32_bf16 v[118:121], v[170:173], v[192:195], v[118:121]
	v_mfma_f32_16x16x32_bf16 v[114:117], v[184:187], v[192:195], v[114:117]
	v_mfma_f32_16x16x32_bf16 v[102:105], v[170:173], v[200:203], v[102:105]
	v_mfma_f32_16x16x32_bf16 v[98:101], v[184:187], v[200:203], v[98:101]
	v_mfma_f32_16x16x32_bf16 v[86:89], v[170:173], v[208:211], v[86:89]
	v_mfma_f32_16x16x32_bf16 v[82:85], v[184:187], v[208:211], v[82:85]
	v_mfma_f32_16x16x32_bf16 v[70:73], v[170:173], v[216:219], v[70:73]
	v_mfma_f32_16x16x32_bf16 v[66:69], v[184:187], v[216:219], v[66:69]
	s_setprio 0
	s_barrier
; #define PG8_STAGE(bufoff, gbase, voff) do { if constexpr (DIAG >= 1) break; _Pragma("unroll") for (int _i = 0; _i < 2; ++_i) \
;         __builtin_amdgcn_global_load_lds((const unsigned*)((const char*)(gbase) + (voff)[_i]), (PG8_LAS unsigned*)(lds + (bufoff) + ldsw + _i * 8192), 16, 0, 0); } while (0)
; #define PG8_LDA(dst, b, h) do { if constexpr (DIAG == 2 || DIAG == 3) break; _Pragma("unroll") for (int m = 0; m < 4; ++m) _Pragma("unroll") for (int k = 0; k < 2; ++k) dst[m][k] = *(const PG8_LAS bf16x8*)(lds + PG8_SA(b, h) + aoff + m * 2048 + k * 1024); } while (0)
; #define PG8_WAIT_V(n) asm volatile("s_waitcnt vmcnt(" #n ")" ::: "memory")
; #define PG8_WAIT_L(n) asm volatile("s_waitcnt lgkmcnt(" #n ")" ::: "memory")
; #define PG8_BAR __builtin_amdgcn_s_barrier()
; #define PG8_LP_OFF __builtin_amdgcn_s_setprio(0)
;     ...
;         for (int t = kb; t < ke; t += 2) {
;             const bool last = (t == ke - 2);
;             const char* a1 = cA + (size_t)(t + 1) * kstep;
;             const char* a2 = last ? nA : cA + (size_t)(t + 2) * kstep; const char* b2 = last ? nB : cB + (size_t)(t + 2) * kstep;
;             const char* a3 = a2 + kstep; const char* b3 = b2 + kstep;
;             if (last && has_next) S.a_ready(nxt);
;             if constexpr (SP2) {
;             PG8_LP_ON; PG8_LDB(B0, 0, 0); PG8_LDB(B1, 0, 1); PG8_SCHED; PG8_LDA(At, 0, 0); PG8_STAGE(PG8_SA(1, 1), a1 + hstep, voffA);
;             PG8_LP_OFF; PG8_WAIT_V(8); PG8_WAIT_L(0); PG8_BAR; PG8_MMA(0, 0, At, B0); PG8_MMA(0, 1, At, B1); PG8_BAR; PG8_SCHED;
;             PG8_LP_ON; PG8_LDA(At, 0, 1); PG8_STAGE(PG8_SB(0, 0), b2, voffB); PG8_STAGE(PG8_SB(0, 1), b2 + hstep, voffB); PG8_STAGE(PG8_SA(0, 0), a2, voffA);
;             PG8_LP_OFF; PG8_WAIT_V(8); PG8_WAIT_L(0); PG8_BAR; PG8_MMA(1, 0, At, B0); PG8_MMA(1, 1, At, B1); PG8_BAR; PG8_SCHED;
;             PG8_LP_ON; PG8_LDB(B0, 1, 0); PG8_LDB(B1, 1, 1); PG8_SCHED; PG8_LDA(At, 1, 0); PG8_STAGE(PG8_SA(0, 1), a2 + hstep, voffA);
;             PG8_LP_OFF; PG8_WAIT_V(8); PG8_WAIT_L(0); PG8_BAR; PG8_MMA(0, 0, At, B0); PG8_MMA(0, 1, At, B1); PG8_BAR; PG8_SCHED;
;             PG8_LP_ON; PG8_LDA(At, 1, 1); PG8_STAGE(PG8_SB(1, 0), b3, voffB); PG8_STAGE(PG8_SB(1, 1), b3 + hstep, voffB); PG8_STAGE(PG8_SA(1, 0), a3, voffA);
;             PG8_LP_OFF; PG8_WAIT_V(8); PG8_WAIT_L(0); PG8_BAR; PG8_MMA(1, 0, At, B0); PG8_MMA(1, 1, At, B1); PG8_BAR; PG8_SCHED;
	ds_read_b128 v[188:191], v179 offset:49152
	ds_read_b128 v[192:195], v179 offset:50176
	ds_read_b128 v[196:199], v179 offset:51200
	ds_read_b128 v[200:203], v179 offset:52224
	ds_read_b128 v[204:207], v179 offset:53248
	ds_read_b128 v[208:211], v179 offset:54272
	ds_read_b128 v[212:215], v179 offset:55296
	ds_read_b128 v[216:219], v179 offset:56320
	s_add_i32 s64, s84, s0
	v_lshl_add_u64 v[160:161], v[160:161], 0, s[14:15]
	s_mov_b32 m0, s64
	s_nop 0
	global_load_lds_dwordx4 v[160:161], off
	s_add_i32 m0, s64, 0x2000
	s_add_u32 s62, s62, 0x100080
	v_lshl_add_u64 v[160:161], v[174:175], 0, s[14:15]
	s_addc_u32 s63, s63, 0
	s_add_i32 s64, s85, s0
	global_load_lds_dwordx4 v[160:161], off
	v_lshl_add_u64 v[160:161], s[62:63], 0, v[146:147]
	s_mov_b32 m0, s64
	s_nop 0
	global_load_lds_dwordx4 v[160:161], off
	v_lshl_add_u64 v[160:161], s[62:63], 0, v[148:149]
	s_add_i32 m0, s64, 0x2000
	s_nop 0
	global_load_lds_dwordx4 v[160:161], off
	s_waitcnt vmcnt(6)
	s_waitcnt lgkmcnt(0)
	s_barrier
	s_setprio 1
	s_waitcnt lgkmcnt(0)
	v_mfma_f32_16x16x32_bf16 v[62:65], v[130:133], v[188:191], v[62:65]
	v_mfma_f32_16x16x32_bf16 v[58:61], v[138:141], v[188:191], v[58:61]
	v_mfma_f32_16x16x32_bf16 v[46:49], v[130:133], v[196:199], v[46:49]
	v_mfma_f32_16x16x32_bf16 v[42:45], v[138:141], v[196:199], v[42:45]
	v_mfma_f32_16x16x32_bf16 v[30:33], v[130:133], v[204:207], v[30:33]
	v_mfma_f32_16x16x32_bf16 v[26:29], v[138:141], v[204:207], v[26:29]
	v_mfma_f32_16x16x32_bf16 v[14:17], v[130:133], v[212:215], v[14:17]
	v_mfma_f32_16x16x32_bf16 v[10:13], v[138:141], v[212:215], v[10:13]
	v_mfma_f32_16x16x32_bf16 v[62:65], v[134:137], v[192:195], v[62:65]
	v_lshl_add_u64 v[160:161], v[220:221], 0, s[14:15]
	s_mov_b32 m0, s74
	s_nop 0
	global_load_lds_dwordx4 v[160:161], off
	v_mfma_f32_16x16x32_bf16 v[58:61], v[142:145], v[192:195], v[58:61]
	v_mfma_f32_16x16x32_bf16 v[46:49], v[134:137], v[200:203], v[46:49]
	v_mfma_f32_16x16x32_bf16 v[42:45], v[142:145], v[200:203], v[42:45]
	v_mfma_f32_16x16x32_bf16 v[30:33], v[134:137], v[208:211], v[30:33]
	v_mfma_f32_16x16x32_bf16 v[26:29], v[142:145], v[208:211], v[26:29]
	v_mfma_f32_16x16x32_bf16 v[14:17], v[134:137], v[216:219], v[14:17]
	v_mfma_f32_16x16x32_bf16 v[10:13], v[142:145], v[216:219], v[10:13]
	s_setprio 0
	s_setprio 1
	v_mfma_f32_16x16x32_bf16 v[54:57], v[166:169], v[188:191], v[54:57]
	v_mfma_f32_16x16x32_bf16 v[50:53], v[180:183], v[188:191], v[50:53]
	v_mfma_f32_16x16x32_bf16 v[38:41], v[166:169], v[196:199], v[38:41]
	v_mfma_f32_16x16x32_bf16 v[34:37], v[180:183], v[196:199], v[34:37]
	v_mfma_f32_16x16x32_bf16 v[22:25], v[166:169], v[204:207], v[22:25]
	v_mfma_f32_16x16x32_bf16 v[18:21], v[180:183], v[204:207], v[18:21]
	v_mfma_f32_16x16x32_bf16 v[6:9], v[166:169], v[212:215], v[6:9]
	v_mfma_f32_16x16x32_bf16 v[2:5], v[180:183], v[212:215], v[2:5]
	v_mfma_f32_16x16x32_bf16 v[54:57], v[170:173], v[192:195], v[54:57]
	v_lshl_add_u64 v[160:161], v[222:223], 0, s[14:15]
	s_mov_b32 m0, s75
	s_nop 0
	global_load_lds_dwordx4 v[160:161], off
	v_mfma_f32_16x16x32_bf16 v[50:53], v[184:187], v[192:195], v[50:53]
	v_mfma_f32_16x16x32_bf16 v[38:41], v[170:173], v[200:203], v[38:41]
	v_mfma_f32_16x16x32_bf16 v[34:37], v[184:187], v[200:203], v[34:37]
	v_mfma_f32_16x16x32_bf16 v[22:25], v[170:173], v[208:211], v[22:25]
	v_mfma_f32_16x16x32_bf16 v[18:21], v[184:187], v[208:211], v[18:21]
	v_mfma_f32_16x16x32_bf16 v[6:9], v[170:173], v[216:219], v[6:9]
	v_mfma_f32_16x16x32_bf16 v[2:5], v[184:187], v[216:219], v[2:5]
	s_setprio 0
	s_barrier
	s_add_i32 s83, s83, 2
	s_add_u32 s60, s60, 0x100
	s_addc_u32 s61, s61, 0
	s_add_u32 s47, s47, 0x100
	s_addc_u32 s82, s82, 0
	s_cmp_gt_u32 s83, 61
	s_cbranch_scc0 .LBB0_725
	s_and_b64 vcc, exec, s[16:17]
	s_cbranch_vccz .LBB0_728
	s_barrier

; #define PG8_STAGE(bufoff, gbase, voff) do { if constexpr (DIAG >= 1) break; _Pragma("unroll") for (int _i = 0; _i < 2; ++_i) \
;         __builtin_amdgcn_global_load_lds((const unsigned*)((const char*)(gbase) + (voff)[_i]), (PG8_LAS unsigned*)(lds + (bufoff) + ldsw + _i * 8192), 16, 0, 0); } while (0)
; #define PG8_LDA(dst, b, h) do { if constexpr (DIAG == 2 || DIAG == 3) break; _Pragma("unroll") for (int m = 0; m < 4; ++m) _Pragma("unroll") for (int k = 0; k < 2; ++k) dst[m][k] = *(const PG8_LAS bf16x8*)(lds + PG8_SA(b, h) + aoff + m * 2048 + k * 1024); } while (0)
; #define PG8_LDB(dst, b, h) do { if constexpr (DIAG == 2 || DIAG == 3) break; _Pragma("unroll") for (int n = 0; n < 2; ++n) _Pragma("unroll") for (int k = 0; k < 2; ++k) dst[n][k] = *(const PG8_LAS bf16x8*)(lds + PG8_SB(b, h) + boff + n * 2048 + k * 1024); } while (0)
; #define PG8_WAIT_V(n) asm volatile("s_waitcnt vmcnt(" #n ")" ::: "memory")
; #define PG8_WAIT_L(n) asm volatile("s_waitcnt lgkmcnt(" #n ")" ::: "memory")
; #define PG8_BAR __builtin_amdgcn_s_barrier()
; #define PG8_LP_ON __builtin_amdgcn_s_setprio(PG8_LOADPRIO)
; #define PG8_LP_OFF __builtin_amdgcn_s_setprio(0)
; #define PG8_LP_ON do {} while (0)
; #define PG8_LP_OFF do {} while (0)
; #define PG8_SCHED __builtin_amdgcn_sched_barrier(0)
;     ...
;         for (int t = kb; t < ke; t += 2) {
;             const bool last = (t == ke - 2);
;             const char* a1 = cA + (size_t)(t + 1) * kstep;
;             const char* a2 = last ? nA : cA + (size_t)(t + 2) * kstep; const char* b2 = last ? nB : cB + (size_t)(t + 2) * kstep;
;             const char* a3 = a2 + kstep; const char* b3 = b2 + kstep;
;             if (last && has_next) S.a_ready(nxt);
;             if constexpr (SP2) {
;             PG8_LP_ON; PG8_LDB(B0, 0, 0); PG8_LDB(B1, 0, 1); PG8_SCHED; PG8_LDA(At, 0, 0); PG8_STAGE(PG8_SA(1, 1), a1 + hstep, voffA);
;             PG8_LP_OFF; PG8_WAIT_V(8); PG8_WAIT_L(0); PG8_BAR; PG8_MMA(0, 0, At, B0); PG8_MMA(0, 1, At, B1); PG8_BAR; PG8_SCHED;
;             PG8_LP_ON; PG8_LDA(At, 0, 1); PG8_STAGE(PG8_SB(0, 0), b2, voffB); PG8_STAGE(PG8_SB(0, 1), b2 + hstep, voffB); PG8_STAGE(PG8_SA(0, 0), a2, voffA);
;             PG8_LP_OFF; PG8_WAIT_V(8); PG8_WAIT_L(0); PG8_BAR; PG8_MMA(1, 0, At, B0); PG8_MMA(1, 1, At, B1); PG8_BAR; PG8_SCHED;
.LBB0_918:
	s_add_i32 s4, s55, 1
	s_ashr_i32 s5, s4, 31
	s_lshl_b64 s[90:91], s[4:5], 7
	s_add_i32 s4, s55, 2
	s_ashr_i32 s5, s4, 31
	s_lshl_b64 s[70:71], s[4:5], 7
	s_add_u32 s5, s22, s70
	s_addc_u32 s72, s23, s71
	s_add_u32 s70, s20, s70
	s_addc_u32 s71, s21, s71
	s_add_i32 s92, 0, 0x10000
	s_cmp_eq_u32 s53, s55
	s_cselect_b32 s73, s26, s72
	s_cselect_b32 s72, s17, s5
	s_cselect_b32 s71, s49, s71
	s_cselect_b32 s70, s27, s70
	s_add_i32 s5, 0, 0x14000
	v_add_u32_e32 v14, s92, v184
	v_add_u32_e32 v30, s5, v184
	ds_read_b128 v[2:5], v14
	ds_read_b128 v[6:9], v14 offset:1024
	ds_read_b128 v[10:13], v14 offset:2048
	ds_read_b128 v[14:17], v14 offset:3072
	ds_read_b128 v[18:21], v30
	ds_read_b128 v[22:25], v30 offset:1024
	ds_read_b128 v[26:29], v30 offset:2048
	ds_read_b128 v[30:33], v30 offset:3072
	ds_read_b128 v[174:177], v216
	ds_read_b128 v[178:181], v216 offset:1024
	ds_read_b128 v[218:221], v216 offset:2048
	ds_read_b128 v[222:225], v216 offset:3072
	ds_read_b128 v[226:229], v216 offset:4096
	ds_read_b128 v[230:233], v216 offset:5120
	ds_read_b128 v[234:237], v216 offset:6144
	ds_read_b128 v[238:241], v216 offset:7168
	s_add_u32 s55, s22, s90
	s_addc_u32 s91, s23, s91
	s_add_u32 s90, s55, 0x80000
	s_addc_u32 s91, s91, 0
	v_lshl_add_u64 v[242:243], s[90:91], 0, v[172:173]
	s_add_i32 m0, s19, 0xc000
	s_nop 0
	global_load_lds_dwordx4 v[242:243], off
	v_lshl_add_u64 v[242:243], s[90:91], 0, v[168:169]
	s_add_i32 m0, s19, 0xe000
	s_nop 0
	global_load_lds_dwordx4 v[242:243], off
	s_waitcnt vmcnt(8)
	s_waitcnt lgkmcnt(0)
	s_barrier
	s_setprio 1
	s_waitcnt lgkmcnt(0)
	v_mfma_f32_16x16x128_f8f6f4 v[158:161], v[2:9], v[174:181], v[158:161]
	v_mfma_f32_16x16x128_f8f6f4 v[154:157], v[10:17], v[174:181], v[154:157]
	v_mfma_f32_16x16x128_f8f6f4 v[150:153], v[2:9], v[218:225], v[150:153]
	v_mfma_f32_16x16x128_f8f6f4 v[146:149], v[10:17], v[218:225], v[146:149]
	v_mfma_f32_16x16x128_f8f6f4 v[142:145], v[2:9], v[226:233], v[142:145]
	v_mfma_f32_16x16x128_f8f6f4 v[138:141], v[10:17], v[226:233], v[138:141]
	v_mfma_f32_16x16x128_f8f6f4 v[134:137], v[2:9], v[234:241], v[134:137]
	v_mfma_f32_16x16x128_f8f6f4 v[130:133], v[10:17], v[234:241], v[130:133]
	s_setprio 0
	s_setprio 1
	v_mfma_f32_16x16x128_f8f6f4 v[126:129], v[18:25], v[174:181], v[126:129]
	v_mfma_f32_16x16x128_f8f6f4 v[122:125], v[26:33], v[174:181], v[122:125]
	v_mfma_f32_16x16x128_f8f6f4 v[118:121], v[18:25], v[218:225], v[118:121]
	v_mfma_f32_16x16x128_f8f6f4 v[114:117], v[26:33], v[218:225], v[114:117]
	v_mfma_f32_16x16x128_f8f6f4 v[110:113], v[18:25], v[226:233], v[110:113]
	v_mfma_f32_16x16x128_f8f6f4 v[106:109], v[26:33], v[226:233], v[106:109]
	v_mfma_f32_16x16x128_f8f6f4 v[102:105], v[18:25], v[234:241], v[102:105]
	v_mfma_f32_16x16x128_f8f6f4 v[98:101], v[26:33], v[234:241], v[98:101]
	s_setprio 0
	s_barrier
	ds_read_b128 v[218:221], v216 offset:16384
	ds_read_b128 v[222:225], v216 offset:17408
	ds_read_b128 v[226:229], v216 offset:18432
	ds_read_b128 v[230:233], v216 offset:19456
	ds_read_b128 v[234:237], v216 offset:20480
	ds_read_b128 v[238:241], v216 offset:21504
	ds_read_b128 v[242:245], v216 offset:22528
	ds_read_b128 v[246:249], v216 offset:23552
	s_add_i32 s55, s92, s45
	v_lshl_add_u64 v[174:175], s[70:71], 0, v[170:171]
	s_mov_b32 m0, s55
	s_nop 0
	global_load_lds_dwordx4 v[174:175], off
	s_add_i32 m0, s55, 0x2000
	s_add_u32 s90, s70, 0x80000
	v_lshl_add_u64 v[176:177], s[70:71], 0, v[166:167]
	s_addc_u32 s91, s71, 0
	s_add_i32 s5, s5, s45
	global_load_lds_dwordx4 v[176:177], off
	v_lshl_add_u64 v[178:179], s[90:91], 0, v[170:171]
	s_mov_b32 m0, s5
	v_lshl_add_u64 v[180:181], s[72:73], 0, v[168:169]
	global_load_lds_dwordx4 v[178:179], off
	v_lshl_add_u64 v[178:179], s[90:91], 0, v[166:167]
	s_add_i32 m0, s5, 0x2000
	s_nop 0
	global_load_lds_dwordx4 v[178:179], off
	s_waitcnt vmcnt(6)
	s_waitcnt lgkmcnt(0)
	s_barrier
	s_setprio 1
	s_waitcnt lgkmcnt(0)
	v_mfma_f32_16x16x128_f8f6f4 v[94:97], v[2:9], v[218:225], v[94:97]
	v_mfma_f32_16x16x128_f8f6f4 v[90:93], v[10:17], v[218:225], v[90:93]
	v_mfma_f32_16x16x128_f8f6f4 v[86:89], v[2:9], v[226:233], v[86:89]
	v_mfma_f32_16x16x128_f8f6f4 v[82:85], v[10:17], v[226:233], v[82:85]
	v_mfma_f32_16x16x128_f8f6f4 v[78:81], v[2:9], v[234:241], v[78:81]
	v_lshl_add_u64 v[178:179], s[72:73], 0, v[172:173]
	s_mov_b32 m0, s19
	s_nop 0
	global_load_lds_dwordx4 v[178:179], off
	v_mfma_f32_16x16x128_f8f6f4 v[74:77], v[10:17], v[234:241], v[74:77]
	v_mfma_f32_16x16x128_f8f6f4 v[70:73], v[2:9], v[242:249], v[70:73]
	v_mfma_f32_16x16x128_f8f6f4 v[66:69], v[10:17], v[242:249], v[66:69]
	s_setprio 0
	s_setprio 1
	v_mfma_f32_16x16x128_f8f6f4 v[62:65], v[18:25], v[218:225], v[62:65]
	v_mfma_f32_16x16x128_f8f6f4 v[58:61], v[26:33], v[218:225], v[58:61]
	v_mfma_f32_16x16x128_f8f6f4 v[54:57], v[18:25], v[226:233], v[54:57]
	v_mfma_f32_16x16x128_f8f6f4 v[50:53], v[26:33], v[226:233], v[50:53]
	v_mfma_f32_16x16x128_f8f6f4 v[46:49], v[18:25], v[234:241], v[46:49]
	s_mov_b32 m0, s47
	s_nop 0
	global_load_lds_dwordx4 v[180:181], off
	v_mfma_f32_16x16x128_f8f6f4 v[42:45], v[26:33], v[234:241], v[42:45]
	v_mfma_f32_16x16x128_f8f6f4 v[38:41], v[18:25], v[242:249], v[38:41]
	v_mfma_f32_16x16x128_f8f6f4 v[34:37], v[26:33], v[242:249], v[34:37]
	s_setprio 0
	s_barrier
; #define PG8_STAGE(bufoff, gbase, voff) do { if constexpr (DIAG >= 1) break; _Pragma("unroll") for (int _i = 0; _i < 2; ++_i) \
;         __builtin_amdgcn_global_load_lds((const unsigned*)((const char*)(gbase) + (voff)[_i]), (PG8_LAS unsigned*)(lds + (bufoff) + ldsw + _i * 8192), 16, 0, 0); } while (0)
; #define PG8_LDA(dst, b, h) do { if constexpr (DIAG == 2 || DIAG == 3) break; _Pragma("unroll") for (int m = 0; m < 4; ++m) _Pragma("unroll") for (int k = 0; k < 2; ++k) dst[m][k] = *(const PG8_LAS bf16x8*)(lds + PG8_SA(b, h) + aoff + m * 2048 + k * 1024); } while (0)
; #define PG8_WAIT_V(n) asm volatile("s_waitcnt vmcnt(" #n ")" ::: "memory")
; #define PG8_WAIT_L(n) asm volatile("s_waitcnt lgkmcnt(" #n ")" ::: "memory")
; #define PG8_BAR __builtin_amdgcn_s_barrier()
; #define PG8_LP_OFF __builtin_amdgcn_s_setprio(0)
;     ...
;         for (int t = kb; t < ke; t += 2) {
;             const bool last = (t == ke - 2);
;             const char* a1 = cA + (size_t)(t + 1) * kstep;
;             const char* a2 = last ? nA : cA + (size_t)(t + 2) * kstep; const char* b2 = last ? nB : cB + (size_t)(t + 2) * kstep;
;             const char* a3 = a2 + kstep; const char* b3 = b2 + kstep;
;             if (last && has_next) S.a_ready(nxt);
;             if constexpr (SP2) {
;             PG8_LP_ON; PG8_LDB(B0, 0, 0); PG8_LDB(B1, 0, 1); PG8_SCHED; PG8_LDA(At, 0, 0); PG8_STAGE(PG8_SA(1, 1), a1 + hstep, voffA);
;             PG8_LP_OFF; PG8_WAIT_V(8); PG8_WAIT_L(0); PG8_BAR; PG8_MMA(0, 0, At, B0); PG8_MMA(0, 1, At, B1); PG8_BAR; PG8_SCHED;
;             PG8_LP_ON; PG8_LDA(At, 0, 1); PG8_STAGE(PG8_SB(0, 0), b2, voffB); PG8_STAGE(PG8_SB(0, 1), b2 + hstep, voffB); PG8_STAGE(PG8_SA(0, 0), a2, voffA);
;             PG8_LP_OFF; PG8_WAIT_V(8); PG8_WAIT_L(0); PG8_BAR; PG8_MMA(1, 0, At, B0); PG8_MMA(1, 1, At, B1); PG8_BAR; PG8_SCHED;
;             PG8_LP_ON; PG8_LDB(B0, 1, 0); PG8_LDB(B1, 1, 1); PG8_SCHED; PG8_LDA(At, 1, 0); PG8_STAGE(PG8_SA(0, 1), a2 + hstep, voffA);
;             PG8_LP_OFF; PG8_WAIT_V(8); PG8_WAIT_L(0); PG8_BAR; PG8_MMA(0, 0, At, B0); PG8_MMA(0, 1, At, B1); PG8_BAR; PG8_SCHED;
;             PG8_LP_ON; PG8_LDA(At, 1, 1); PG8_STAGE(PG8_SB(1, 0), b3, voffB); PG8_STAGE(PG8_SB(1, 1), b3 + hstep, voffB); PG8_STAGE(PG8_SA(1, 0), a3, voffA);
;             PG8_LP_OFF; PG8_WAIT_V(8); PG8_WAIT_L(0); PG8_BAR; PG8_MMA(1, 0, At, B0); PG8_MMA(1, 1, At, B1); PG8_BAR; PG8_SCHED;
	s_add_i32 s5, 0, 0x18000
	s_add_i32 s55, 0, 0x1c000
	v_add_u32_e32 v2, s5, v184
	v_add_u32_e32 v6, s55, v184
	ds_read_b128 v[26:29], v2
	ds_read_b128 v[30:33], v2 offset:1024
	ds_read_b128 v[18:21], v2 offset:2048
	ds_read_b128 v[22:25], v2 offset:3072
	ds_read_b128 v[10:13], v6
	ds_read_b128 v[14:17], v6 offset:1024
	ds_read_b128 v[2:5], v6 offset:2048
	ds_read_b128 v[6:9], v6 offset:3072
	ds_read_b128 v[218:221], v216 offset:32768
	ds_read_b128 v[222:225], v216 offset:33792
	ds_read_b128 v[226:229], v216 offset:34816
	ds_read_b128 v[230:233], v216 offset:35840
	ds_read_b128 v[234:237], v216 offset:36864
	ds_read_b128 v[238:241], v216 offset:37888
	ds_read_b128 v[242:245], v216 offset:38912
	ds_read_b128 v[246:249], v216 offset:39936
	s_add_u32 s72, s72, 0x80000
	s_addc_u32 s73, s73, 0
	s_mov_b32 m0, s74
	v_lshl_add_u64 v[250:251], s[72:73], 0, v[172:173]
	global_load_lds_dwordx4 v[250:251], off
	v_lshl_add_u64 v[250:251], s[72:73], 0, v[168:169]
	s_mov_b32 m0, s75
	s_nop 0
	global_load_lds_dwordx4 v[250:251], off
	s_waitcnt vmcnt(8)
	s_waitcnt lgkmcnt(0)
	s_barrier
	s_setprio 1
	s_waitcnt lgkmcnt(0)
	v_mfma_f32_16x16x128_f8f6f4 v[158:161], v[26:33], v[218:225], v[158:161]
	v_mfma_f32_16x16x128_f8f6f4 v[154:157], v[18:25], v[218:225], v[154:157]
	v_mfma_f32_16x16x128_f8f6f4 v[150:153], v[26:33], v[226:233], v[150:153]
	v_mfma_f32_16x16x128_f8f6f4 v[146:149], v[18:25], v[226:233], v[146:149]
	v_mfma_f32_16x16x128_f8f6f4 v[142:145], v[26:33], v[234:241], v[142:145]
	v_mfma_f32_16x16x128_f8f6f4 v[138:141], v[18:25], v[234:241], v[138:141]
	v_mfma_f32_16x16x128_f8f6f4 v[134:137], v[26:33], v[242:249], v[134:137]
	v_mfma_f32_16x16x128_f8f6f4 v[130:133], v[18:25], v[242:249], v[130:133]
	s_setprio 0
	s_setprio 1
	v_mfma_f32_16x16x128_f8f6f4 v[126:129], v[10:17], v[218:225], v[126:129]
	v_mfma_f32_16x16x128_f8f6f4 v[122:125], v[2:9], v[218:225], v[122:125]
	v_mfma_f32_16x16x128_f8f6f4 v[118:121], v[10:17], v[226:233], v[118:121]
	v_mfma_f32_16x16x128_f8f6f4 v[114:117], v[2:9], v[226:233], v[114:117]
	v_mfma_f32_16x16x128_f8f6f4 v[110:113], v[10:17], v[234:241], v[110:113]
	v_mfma_f32_16x16x128_f8f6f4 v[106:109], v[2:9], v[234:241], v[106:109]
	v_mfma_f32_16x16x128_f8f6f4 v[102:105], v[10:17], v[242:249], v[102:105]
	v_mfma_f32_16x16x128_f8f6f4 v[98:101], v[2:9], v[242:249], v[98:101]
	s_setprio 0
	s_barrier
	ds_read_b128 v[218:221], v216 offset:49152
	ds_read_b128 v[222:225], v216 offset:50176
	ds_read_b128 v[226:229], v216 offset:51200
	ds_read_b128 v[230:233], v216 offset:52224
	ds_read_b128 v[234:237], v216 offset:53248
	ds_read_b128 v[238:241], v216 offset:54272
	ds_read_b128 v[242:245], v216 offset:55296
	ds_read_b128 v[246:249], v216 offset:56320
	s_add_i32 s5, s5, s45
	v_lshl_add_u64 v[174:175], v[174:175], 0, s[40:41]
	s_mov_b32 m0, s5
	s_nop 0
	global_load_lds_dwordx4 v[174:175], off
	s_add_i32 m0, s5, 0x2000
	s_add_u32 s70, s70, 0x80080
	v_lshl_add_u64 v[174:175], v[176:177], 0, s[40:41]
	s_addc_u32 s71, s71, 0
	s_add_i32 s5, s55, s45
	global_load_lds_dwordx4 v[174:175], off
	v_lshl_add_u64 v[174:175], s[70:71], 0, v[170:171]
	s_mov_b32 m0, s5
	s_nop 0
	global_load_lds_dwordx4 v[174:175], off
	v_lshl_add_u64 v[174:175], s[70:71], 0, v[166:167]
	s_add_i32 m0, s5, 0x2000
	s_nop 0
	global_load_lds_dwordx4 v[174:175], off
	s_waitcnt vmcnt(6)
	s_waitcnt lgkmcnt(0)
	s_barrier
	s_setprio 1
	s_waitcnt lgkmcnt(0)
	v_mfma_f32_16x16x128_f8f6f4 v[94:97], v[26:33], v[218:225], v[94:97]
	v_mfma_f32_16x16x128_f8f6f4 v[90:93], v[18:25], v[218:225], v[90:93]
	v_mfma_f32_16x16x128_f8f6f4 v[86:89], v[26:33], v[226:233], v[86:89]
	v_mfma_f32_16x16x128_f8f6f4 v[82:85], v[18:25], v[226:233], v[82:85]
	v_mfma_f32_16x16x128_f8f6f4 v[78:81], v[26:33], v[234:241], v[78:81]
	v_lshl_add_u64 v[174:175], v[178:179], 0, s[40:41]
	s_mov_b32 m0, s82
	s_nop 0
	global_load_lds_dwordx4 v[174:175], off
	v_mfma_f32_16x16x128_f8f6f4 v[74:77], v[18:25], v[234:241], v[74:77]
	v_mfma_f32_16x16x128_f8f6f4 v[70:73], v[26:33], v[242:249], v[70:73]
	v_mfma_f32_16x16x128_f8f6f4 v[66:69], v[18:25], v[242:249], v[66:69]
	s_setprio 0
	s_setprio 1
	v_mfma_f32_16x16x128_f8f6f4 v[62:65], v[10:17], v[218:225], v[62:65]
	v_mfma_f32_16x16x128_f8f6f4 v[58:61], v[2:9], v[218:225], v[58:61]
	v_mfma_f32_16x16x128_f8f6f4 v[54:57], v[10:17], v[226:233], v[54:57]
	v_mfma_f32_16x16x128_f8f6f4 v[50:53], v[2:9], v[226:233], v[50:53]
	v_mfma_f32_16x16x128_f8f6f4 v[46:49], v[10:17], v[234:241], v[46:49]
	v_lshl_add_u64 v[174:175], v[180:181], 0, s[40:41]
	s_mov_b32 m0, s83
	s_nop 0
	global_load_lds_dwordx4 v[174:175], off
	v_mfma_f32_16x16x128_f8f6f4 v[42:45], v[2:9], v[234:241], v[42:45]
	v_mfma_f32_16x16x128_f8f6f4 v[38:41], v[10:17], v[242:249], v[38:41]
	v_mfma_f32_16x16x128_f8f6f4 v[34:37], v[2:9], v[242:249], v[34:37]
	s_setprio 0
	s_barrier
	s_cmp_ge_i32 s4, s79
	s_mov_b32 s55, s4
	s_cbranch_scc0 .LBB0_918

; #define PG8_STAGE(bufoff, gbase, voff) do { if constexpr (DIAG >= 1) break; _Pragma("unroll") for (int _i = 0; _i < 2; ++_i) \
;         __builtin_amdgcn_global_load_lds((const unsigned*)((const char*)(gbase) + (voff)[_i]), (PG8_LAS unsigned*)(lds + (bufoff) + ldsw + _i * 8192), 16, 0, 0); } while (0)
; #define PG8_LDA(dst, b, h) do { if constexpr (DIAG == 2 || DIAG == 3) break; _Pragma("unroll") for (int m = 0; m < 4; ++m) _Pragma("unroll") for (int k = 0; k < 2; ++k) dst[m][k] = *(const PG8_LAS bf16x8*)(lds + PG8_SA(b, h) + aoff + m * 2048 + k * 1024); } while (0)
; #define PG8_LDB(dst, b, h) do { if constexpr (DIAG == 2 || DIAG == 3) break; _Pragma("unroll") for (int n = 0; n < 2; ++n) _Pragma("unroll") for (int k = 0; k < 2; ++k) dst[n][k] = *(const PG8_LAS bf16x8*)(lds + PG8_SB(b, h) + boff + n * 2048 + k * 1024); } while (0)
; #define PG8_WAIT_V(n) asm volatile("s_waitcnt vmcnt(" #n ")" ::: "memory")
; #define PG8_WAIT_L(n) asm volatile("s_waitcnt lgkmcnt(" #n ")" ::: "memory")
; #define PG8_BAR __builtin_amdgcn_s_barrier()
; #define PG8_LP_ON __builtin_amdgcn_s_setprio(PG8_LOADPRIO)
; #define PG8_LP_OFF __builtin_amdgcn_s_setprio(0)
; #define PG8_LP_ON do {} while (0)
; #define PG8_LP_OFF do {} while (0)
; #define PG8_SCHED __builtin_amdgcn_sched_barrier(0)
;     ...
;         for (int t = kb; t < ke; t += 2) {
;             const bool last = (t == ke - 2);
;             const char* a1 = cA + (size_t)(t + 1) * kstep;
;             const char* a2 = last ? nA : cA + (size_t)(t + 2) * kstep; const char* b2 = last ? nB : cB + (size_t)(t + 2) * kstep;
;             const char* a3 = a2 + kstep; const char* b3 = b2 + kstep;
;             if (last && has_next) S.a_ready(nxt);
;             if constexpr (SP2) {
;             PG8_LP_ON; PG8_LDB(B0, 0, 0); PG8_LDB(B1, 0, 1); PG8_SCHED; PG8_LDA(At, 0, 0); PG8_STAGE(PG8_SA(1, 1), a1 + hstep, voffA);
;             PG8_LP_OFF; PG8_WAIT_V(8); PG8_WAIT_L(0); PG8_BAR; PG8_MMA(0, 0, At, B0); PG8_MMA(0, 1, At, B1); PG8_BAR; PG8_SCHED;
;             PG8_LP_ON; PG8_LDA(At, 0, 1); PG8_STAGE(PG8_SB(0, 0), b2, voffB); PG8_STAGE(PG8_SB(0, 1), b2 + hstep, voffB); PG8_STAGE(PG8_SA(0, 0), a2, voffA);
;             PG8_LP_OFF; PG8_WAIT_V(8); PG8_WAIT_L(0); PG8_BAR; PG8_MMA(1, 0, At, B0); PG8_MMA(1, 1, At, B1); PG8_BAR; PG8_SCHED;
.LBB0_1034:
	s_add_i32 s6, s8, 1
	s_ashr_i32 s7, s6, 31
	s_lshl_b64 s[88:89], s[6:7], 7
	s_add_i32 s6, s8, 2
	s_ashr_i32 s7, s6, 31
	s_lshl_b64 s[60:61], s[6:7], 7
	s_add_u32 s7, s24, s60
	s_addc_u32 s9, s25, s61
	s_add_u32 s90, s22, s60
	s_addc_u32 s91, s23, s61
	s_add_i32 s92, 0, 0x10000
	s_cmp_eq_u32 s87, s8
	s_cselect_b32 s61, s26, s9
	s_cselect_b32 s60, s19, s7
	s_cselect_b32 s9, s47, s91
	s_cselect_b32 s8, s27, s90
	s_add_i32 s7, 0, 0x14000
	v_add_u32_e32 v14, s92, v181
	v_add_u32_e32 v30, s7, v181
	ds_read_b128 v[2:5], v14
	ds_read_b128 v[6:9], v14 offset:1024
	ds_read_b128 v[10:13], v14 offset:2048
	ds_read_b128 v[14:17], v14 offset:3072
	ds_read_b128 v[18:21], v30
	ds_read_b128 v[22:25], v30 offset:1024
	ds_read_b128 v[26:29], v30 offset:2048
	ds_read_b128 v[30:33], v30 offset:3072
	ds_read_b128 v[172:175], v213
	ds_read_b128 v[176:179], v213 offset:1024
	ds_read_b128 v[214:217], v213 offset:2048
	ds_read_b128 v[218:221], v213 offset:3072
	ds_read_b128 v[222:225], v213 offset:4096
	ds_read_b128 v[226:229], v213 offset:5120
	ds_read_b128 v[230:233], v213 offset:6144
	ds_read_b128 v[234:237], v213 offset:7168
	s_add_u32 s88, s24, s88
	s_addc_u32 s89, s25, s89
	s_add_u32 s88, s88, 0x158000
	s_addc_u32 s89, s89, 0
	v_lshl_add_u64 v[238:239], s[88:89], 0, v[166:167]
	s_add_i32 m0, s66, 0xc000
	s_nop 0
	global_load_lds_dwordx4 v[238:239], off
	v_lshl_add_u64 v[238:239], s[88:89], 0, v[168:169]
	s_add_i32 m0, s66, 0xe000
	s_nop 0
	global_load_lds_dwordx4 v[238:239], off
	s_waitcnt vmcnt(8)
	s_waitcnt lgkmcnt(0)
	s_barrier
	s_setprio 1
	s_waitcnt lgkmcnt(0)
	v_mfma_f32_16x16x128_f8f6f4 v[158:161], v[2:9], v[172:179], v[158:161]
	v_mfma_f32_16x16x128_f8f6f4 v[154:157], v[10:17], v[172:179], v[154:157]
	v_mfma_f32_16x16x128_f8f6f4 v[150:153], v[2:9], v[214:221], v[150:153]
	v_mfma_f32_16x16x128_f8f6f4 v[146:149], v[10:17], v[214:221], v[146:149]
	v_mfma_f32_16x16x128_f8f6f4 v[142:145], v[2:9], v[222:229], v[142:145]
	v_mfma_f32_16x16x128_f8f6f4 v[138:141], v[10:17], v[222:229], v[138:141]
	v_mfma_f32_16x16x128_f8f6f4 v[134:137], v[2:9], v[230:237], v[134:137]
	v_mfma_f32_16x16x128_f8f6f4 v[130:133], v[10:17], v[230:237], v[130:133]
	s_setprio 0
	s_setprio 1
	v_mfma_f32_16x16x128_f8f6f4 v[126:129], v[18:25], v[172:179], v[126:129]
	v_mfma_f32_16x16x128_f8f6f4 v[122:125], v[26:33], v[172:179], v[122:125]
	v_mfma_f32_16x16x128_f8f6f4 v[118:121], v[18:25], v[214:221], v[118:121]
	v_mfma_f32_16x16x128_f8f6f4 v[114:117], v[26:33], v[214:221], v[114:117]
	v_mfma_f32_16x16x128_f8f6f4 v[110:113], v[18:25], v[222:229], v[110:113]
	v_mfma_f32_16x16x128_f8f6f4 v[106:109], v[26:33], v[222:229], v[106:109]
	v_mfma_f32_16x16x128_f8f6f4 v[102:105], v[18:25], v[230:237], v[102:105]
	v_mfma_f32_16x16x128_f8f6f4 v[98:101], v[26:33], v[230:237], v[98:101]
	s_setprio 0
	s_barrier
	ds_read_b128 v[214:217], v213 offset:16384
	ds_read_b128 v[218:221], v213 offset:17408
	ds_read_b128 v[222:225], v213 offset:18432
	ds_read_b128 v[226:229], v213 offset:19456
	ds_read_b128 v[230:233], v213 offset:20480
	ds_read_b128 v[234:237], v213 offset:21504
	ds_read_b128 v[238:241], v213 offset:22528
	ds_read_b128 v[242:245], v213 offset:23552
	s_add_i32 s88, s92, s65
	v_lshl_add_u64 v[172:173], s[8:9], 0, v[166:167]
	s_mov_b32 m0, s88
	s_nop 0
	global_load_lds_dwordx4 v[172:173], off
	s_add_i32 m0, s88, 0x2000
	s_add_u32 s88, s8, 0x158000
	v_lshl_add_u64 v[174:175], s[8:9], 0, v[168:169]
	s_addc_u32 s89, s9, 0
	s_add_i32 s7, s7, s65
	global_load_lds_dwordx4 v[174:175], off
	v_lshl_add_u64 v[176:177], s[88:89], 0, v[166:167]
	s_mov_b32 m0, s7
	v_lshl_add_u64 v[178:179], s[60:61], 0, v[168:169]
	global_load_lds_dwordx4 v[176:177], off
	v_lshl_add_u64 v[176:177], s[88:89], 0, v[168:169]
	s_add_i32 m0, s7, 0x2000
	s_nop 0
	global_load_lds_dwordx4 v[176:177], off
	s_waitcnt vmcnt(6)
	s_waitcnt lgkmcnt(0)
	s_barrier
	s_setprio 1
	s_waitcnt lgkmcnt(0)
	v_mfma_f32_16x16x128_f8f6f4 v[94:97], v[2:9], v[214:221], v[94:97]
	v_mfma_f32_16x16x128_f8f6f4 v[90:93], v[10:17], v[214:221], v[90:93]
	v_mfma_f32_16x16x128_f8f6f4 v[86:89], v[2:9], v[222:229], v[86:89]
	v_mfma_f32_16x16x128_f8f6f4 v[82:85], v[10:17], v[222:229], v[82:85]
	v_mfma_f32_16x16x128_f8f6f4 v[78:81], v[2:9], v[230:237], v[78:81]
	v_lshl_add_u64 v[176:177], s[60:61], 0, v[166:167]
	s_mov_b32 m0, s66
	s_nop 0
	global_load_lds_dwordx4 v[176:177], off
	v_mfma_f32_16x16x128_f8f6f4 v[74:77], v[10:17], v[230:237], v[74:77]
	v_mfma_f32_16x16x128_f8f6f4 v[70:73], v[2:9], v[238:245], v[70:73]
	v_mfma_f32_16x16x128_f8f6f4 v[66:69], v[10:17], v[238:245], v[66:69]
	s_setprio 0
	s_setprio 1
	v_mfma_f32_16x16x128_f8f6f4 v[62:65], v[18:25], v[214:221], v[62:65]
	v_mfma_f32_16x16x128_f8f6f4 v[58:61], v[26:33], v[214:221], v[58:61]
	v_mfma_f32_16x16x128_f8f6f4 v[54:57], v[18:25], v[222:229], v[54:57]
	v_mfma_f32_16x16x128_f8f6f4 v[50:53], v[26:33], v[222:229], v[50:53]
	v_mfma_f32_16x16x128_f8f6f4 v[46:49], v[18:25], v[230:237], v[46:49]
	s_mov_b32 m0, s67
	s_nop 0
	global_load_lds_dwordx4 v[178:179], off
	v_mfma_f32_16x16x128_f8f6f4 v[42:45], v[26:33], v[230:237], v[42:45]
	v_mfma_f32_16x16x128_f8f6f4 v[38:41], v[18:25], v[238:245], v[38:41]
	v_mfma_f32_16x16x128_f8f6f4 v[34:37], v[26:33], v[238:245], v[34:37]
	s_setprio 0
	s_barrier
; #define PG8_STAGE(bufoff, gbase, voff) do { if constexpr (DIAG >= 1) break; _Pragma("unroll") for (int _i = 0; _i < 2; ++_i) \
;         __builtin_amdgcn_global_load_lds((const unsigned*)((const char*)(gbase) + (voff)[_i]), (PG8_LAS unsigned*)(lds + (bufoff) + ldsw + _i * 8192), 16, 0, 0); } while (0)
; #define PG8_LDA(dst, b, h) do { if constexpr (DIAG == 2 || DIAG == 3) break; _Pragma("unroll") for (int m = 0; m < 4; ++m) _Pragma("unroll") for (int k = 0; k < 2; ++k) dst[m][k] = *(const PG8_LAS bf16x8*)(lds + PG8_SA(b, h) + aoff + m * 2048 + k * 1024); } while (0)
; #define PG8_WAIT_V(n) asm volatile("s_waitcnt vmcnt(" #n ")" ::: "memory")
; #define PG8_WAIT_L(n) asm volatile("s_waitcnt lgkmcnt(" #n ")" ::: "memory")
; #define PG8_BAR __builtin_amdgcn_s_barrier()
; #define PG8_LP_OFF __builtin_amdgcn_s_setprio(0)
;     ...
;         for (int t = kb; t < ke; t += 2) {
;             const bool last = (t == ke - 2);
;             const char* a1 = cA + (size_t)(t + 1) * kstep;
;             const char* a2 = last ? nA : cA + (size_t)(t + 2) * kstep; const char* b2 = last ? nB : cB + (size_t)(t + 2) * kstep;
;             const char* a3 = a2 + kstep; const char* b3 = b2 + kstep;
;             if (last && has_next) S.a_ready(nxt);
;             if constexpr (SP2) {
;             PG8_LP_ON; PG8_LDB(B0, 0, 0); PG8_LDB(B1, 0, 1); PG8_SCHED; PG8_LDA(At, 0, 0); PG8_STAGE(PG8_SA(1, 1), a1 + hstep, voffA);
;             PG8_LP_OFF; PG8_WAIT_V(8); PG8_WAIT_L(0); PG8_BAR; PG8_MMA(0, 0, At, B0); PG8_MMA(0, 1, At, B1); PG8_BAR; PG8_SCHED;
;             PG8_LP_ON; PG8_LDA(At, 0, 1); PG8_STAGE(PG8_SB(0, 0), b2, voffB); PG8_STAGE(PG8_SB(0, 1), b2 + hstep, voffB); PG8_STAGE(PG8_SA(0, 0), a2, voffA);
;             PG8_LP_OFF; PG8_WAIT_V(8); PG8_WAIT_L(0); PG8_BAR; PG8_MMA(1, 0, At, B0); PG8_MMA(1, 1, At, B1); PG8_BAR; PG8_SCHED;
;             PG8_LP_ON; PG8_LDB(B0, 1, 0); PG8_LDB(B1, 1, 1); PG8_SCHED; PG8_LDA(At, 1, 0); PG8_STAGE(PG8_SA(0, 1), a2 + hstep, voffA);
;             PG8_LP_OFF; PG8_WAIT_V(8); PG8_WAIT_L(0); PG8_BAR; PG8_MMA(0, 0, At, B0); PG8_MMA(0, 1, At, B1); PG8_BAR; PG8_SCHED;
;             PG8_LP_ON; PG8_LDA(At, 1, 1); PG8_STAGE(PG8_SB(1, 0), b3, voffB); PG8_STAGE(PG8_SB(1, 1), b3 + hstep, voffB); PG8_STAGE(PG8_SA(1, 0), a3, voffA);
;             PG8_LP_OFF; PG8_WAIT_V(8); PG8_WAIT_L(0); PG8_BAR; PG8_MMA(1, 0, At, B0); PG8_MMA(1, 1, At, B1); PG8_BAR; PG8_SCHED;
	s_add_i32 s7, 0, 0x18000
	s_add_i32 s88, 0, 0x1c000
	v_add_u32_e32 v2, s7, v181
	v_add_u32_e32 v6, s88, v181
	ds_read_b128 v[26:29], v2
	ds_read_b128 v[30:33], v2 offset:1024
	ds_read_b128 v[18:21], v2 offset:2048
	ds_read_b128 v[22:25], v2 offset:3072
	ds_read_b128 v[10:13], v6
	ds_read_b128 v[14:17], v6 offset:1024
	ds_read_b128 v[2:5], v6 offset:2048
	ds_read_b128 v[6:9], v6 offset:3072
	ds_read_b128 v[214:217], v213 offset:32768
	ds_read_b128 v[218:221], v213 offset:33792
	ds_read_b128 v[222:225], v213 offset:34816
	ds_read_b128 v[226:229], v213 offset:35840
	ds_read_b128 v[230:233], v213 offset:36864
	ds_read_b128 v[234:237], v213 offset:37888
	ds_read_b128 v[238:241], v213 offset:38912
	ds_read_b128 v[242:245], v213 offset:39936
	s_add_u32 s60, s60, 0x158000
	s_addc_u32 s61, s61, 0
	s_mov_b32 m0, s70
	v_lshl_add_u64 v[246:247], s[60:61], 0, v[166:167]
	global_load_lds_dwordx4 v[246:247], off
	v_lshl_add_u64 v[246:247], s[60:61], 0, v[168:169]
	s_mov_b32 m0, s71
	s_nop 0
	global_load_lds_dwordx4 v[246:247], off
	s_waitcnt vmcnt(8)
	s_waitcnt lgkmcnt(0)
	s_barrier
	s_setprio 1
	s_waitcnt lgkmcnt(0)
	v_mfma_f32_16x16x128_f8f6f4 v[158:161], v[26:33], v[214:221], v[158:161]
	v_mfma_f32_16x16x128_f8f6f4 v[154:157], v[18:25], v[214:221], v[154:157]
	v_mfma_f32_16x16x128_f8f6f4 v[150:153], v[26:33], v[222:229], v[150:153]
	v_mfma_f32_16x16x128_f8f6f4 v[146:149], v[18:25], v[222:229], v[146:149]
	v_mfma_f32_16x16x128_f8f6f4 v[142:145], v[26:33], v[230:237], v[142:145]
	v_mfma_f32_16x16x128_f8f6f4 v[138:141], v[18:25], v[230:237], v[138:141]
	v_mfma_f32_16x16x128_f8f6f4 v[134:137], v[26:33], v[238:245], v[134:137]
	v_mfma_f32_16x16x128_f8f6f4 v[130:133], v[18:25], v[238:245], v[130:133]
	s_setprio 0
	s_setprio 1
	v_mfma_f32_16x16x128_f8f6f4 v[126:129], v[10:17], v[214:221], v[126:129]
	v_mfma_f32_16x16x128_f8f6f4 v[122:125], v[2:9], v[214:221], v[122:125]
	v_mfma_f32_16x16x128_f8f6f4 v[118:121], v[10:17], v[222:229], v[118:121]
	v_mfma_f32_16x16x128_f8f6f4 v[114:117], v[2:9], v[222:229], v[114:117]
	v_mfma_f32_16x16x128_f8f6f4 v[110:113], v[10:17], v[230:237], v[110:113]
	v_mfma_f32_16x16x128_f8f6f4 v[106:109], v[2:9], v[230:237], v[106:109]
	v_mfma_f32_16x16x128_f8f6f4 v[102:105], v[10:17], v[238:245], v[102:105]
	v_mfma_f32_16x16x128_f8f6f4 v[98:101], v[2:9], v[238:245], v[98:101]
	s_setprio 0
	s_barrier
	ds_read_b128 v[214:217], v213 offset:49152
	ds_read_b128 v[218:221], v213 offset:50176
	ds_read_b128 v[222:225], v213 offset:51200
	ds_read_b128 v[226:229], v213 offset:52224
	ds_read_b128 v[230:233], v213 offset:53248
	ds_read_b128 v[234:237], v213 offset:54272
	ds_read_b128 v[238:241], v213 offset:55296
	ds_read_b128 v[242:245], v213 offset:56320
	s_add_i32 s7, s7, s65
	v_lshl_add_u64 v[172:173], v[172:173], 0, s[40:41]
	s_mov_b32 m0, s7
	s_nop 0
	global_load_lds_dwordx4 v[172:173], off
	s_add_i32 m0, s7, 0x2000
	s_add_u32 s8, s8, 0x158080
	v_lshl_add_u64 v[172:173], v[174:175], 0, s[40:41]
	s_addc_u32 s9, s9, 0
	s_add_i32 s7, s88, s65
	global_load_lds_dwordx4 v[172:173], off
	v_lshl_add_u64 v[172:173], s[8:9], 0, v[166:167]
	s_mov_b32 m0, s7
	s_nop 0
	global_load_lds_dwordx4 v[172:173], off
	v_lshl_add_u64 v[172:173], s[8:9], 0, v[168:169]
	s_add_i32 m0, s7, 0x2000
	s_nop 0
	global_load_lds_dwordx4 v[172:173], off
	s_waitcnt vmcnt(6)
	s_waitcnt lgkmcnt(0)
	s_barrier
	s_setprio 1
	s_waitcnt lgkmcnt(0)
	v_mfma_f32_16x16x128_f8f6f4 v[94:97], v[26:33], v[214:221], v[94:97]
	v_mfma_f32_16x16x128_f8f6f4 v[90:93], v[18:25], v[214:221], v[90:93]
	v_mfma_f32_16x16x128_f8f6f4 v[86:89], v[26:33], v[222:229], v[86:89]
	v_mfma_f32_16x16x128_f8f6f4 v[82:85], v[18:25], v[222:229], v[82:85]
	v_mfma_f32_16x16x128_f8f6f4 v[78:81], v[26:33], v[230:237], v[78:81]
	v_lshl_add_u64 v[172:173], v[176:177], 0, s[40:41]
	s_mov_b32 m0, s77
	s_nop 0
	global_load_lds_dwordx4 v[172:173], off
	v_mfma_f32_16x16x128_f8f6f4 v[74:77], v[18:25], v[230:237], v[74:77]
	v_mfma_f32_16x16x128_f8f6f4 v[70:73], v[26:33], v[238:245], v[70:73]
	v_mfma_f32_16x16x128_f8f6f4 v[66:69], v[18:25], v[238:245], v[66:69]
	s_setprio 0
	s_setprio 1
	v_mfma_f32_16x16x128_f8f6f4 v[62:65], v[10:17], v[214:221], v[62:65]
	v_mfma_f32_16x16x128_f8f6f4 v[58:61], v[2:9], v[214:221], v[58:61]
	v_mfma_f32_16x16x128_f8f6f4 v[54:57], v[10:17], v[222:229], v[54:57]
	v_mfma_f32_16x16x128_f8f6f4 v[50:53], v[2:9], v[222:229], v[50:53]
	v_mfma_f32_16x16x128_f8f6f4 v[46:49], v[10:17], v[230:237], v[46:49]
	v_lshl_add_u64 v[172:173], v[178:179], 0, s[40:41]
	s_mov_b32 m0, s78
	s_nop 0
	global_load_lds_dwordx4 v[172:173], off
	v_mfma_f32_16x16x128_f8f6f4 v[42:45], v[2:9], v[230:237], v[42:45]
	v_mfma_f32_16x16x128_f8f6f4 v[38:41], v[10:17], v[238:245], v[38:41]
	v_mfma_f32_16x16x128_f8f6f4 v[34:37], v[2:9], v[238:245], v[34:37]
	s_setprio 0
	s_barrier
	s_cmp_ge_i32 s6, s64
	s_mov_b32 s8, s6
	s_cbranch_scc0 .LBB0_1034
	v_readlane_b32 s94, v252, 39
	v_readlane_b32 s95, v252, 40
